# G3 epilogue: first column's conv coefficients fetched at the start of the epilogue instead of at the head of the column loop
# baseline (speedup 1.0000x reference)
; __device__ __forceinline__ float bperm_f(int src_lane, float v) { return __builtin_bit_cast(float, __builtin_amdgcn_ds_bpermute(src_lane << 2, __builtin_bit_cast(int, v))); }
;     __device__ __forceinline__ void operator()(Acc& acc, const Unit& u, int wr, int wc, int fr, int fq) const {
;         const int b = u.pm / UPU, j = u.pm % UPU;
;         const int tbase = 252 * j + 126 * wr - 2 + fr;
;         const int ch0 = 128 * u.pn + 32 * wc + 8 * fq;
;         float chain = 0.f;
;         { const int ln = (fq << 4) | fr; f32x4 pq[8];
; #pragma unroll
;           for (int q = 0; q < 8; ++q) { const int t = tbase + 16 * q; const bool ok = (t >= 0) && (t < SEQ); pq[q] = *(const f32x4*)(ssq + (size_t)(b * SEQ + (ok ? t : 0)) * 16 + 4 * fq); }
; #pragma unroll
;           for (int q = 0; q < 8; ++q) {
;             const int t = tbase + 16 * q; const bool ok = (t >= 0) && (t < SEQ);
;             float sq = (pq[q][0] + pq[q][1]) + (pq[q][2] + pq[q][3]); sq += bperm_f(ln ^ 16, sq); sq += bperm_f(ln ^ 32, sq);
;             const float rs = rsqrtf(sq * (1.0f / DM) + EPS);
; #pragma unroll
;             for (int bj = 0; bj < 2; ++bj)
; #pragma unroll
;                 for (int n = 0; n < 2; ++n)
; #pragma unroll
;                     for (int i = 0; i < 4; ++i) { const float v = acc[q >> 2][bj][q & 3][n][i]; acc[q >> 2][bj][q & 3][n][i] = ok ? v * rs : 0.f; }
;     ...
;                 const float g0 = cw[cg_], g1 = cw[NUP + cg_], g2 = cw[2 * NUP + cg_], gb = cb[cg_];
;                 const float v0 = cw[cv_], v1 = cw[NUP + cv_], v2 = cw[2 * NUP + cv_], vb = cb[cv_];
.LBB0_43:
	v_lshl_or_b32 v248, s34, 7, v2
	v_ashrrev_i32_e32 v249, 31, v248
	v_lshlrev_b64 v[248:249], 2, v[248:249]
	v_lshl_add_u64 v[250:251], s[36:37], 0, v[248:249]
	v_lshl_add_u64 v[248:249], s[60:61], 0, v[248:249]
	global_load_dword v240, v[250:251], off
	s_movk_i32 s21, 0x5000
	v_add_co_u32_e32 v252, vcc, s21, v250
	s_nop 1
	v_addc_co_u32_e32 v253, vcc, 0, v251, vcc
	global_load_dword v241, v[252:253], off offset:2048
	s_mov_b32 s21, 0xb000
	v_add_co_u32_e32 v252, vcc, s21, v250
	s_nop 1
	v_addc_co_u32_e32 v253, vcc, 0, v251, vcc
	global_load_dword v242, v[252:253], off
	global_load_dword v243, v[248:249], off
	v_add_co_u32_e32 v252, vcc, s97, v250
	s_nop 1
	v_addc_co_u32_e32 v253, vcc, 0, v251, vcc
	global_load_dword v244, v[252:253], off offset:3072
	v_add_co_u32_e32 v252, vcc, s97, v248
	s_nop 1
	v_addc_co_u32_e32 v253, vcc, 0, v249, vcc
	global_load_dword v245, v[252:253], off offset:3072
	v_add_co_u32_e32 v252, vcc, s80, v250
	s_nop 1
	v_addc_co_u32_e32 v253, vcc, 0, v251, vcc
	global_load_dword v246, v[252:253], off offset:1024
	s_mov_b32 s21, 0xd000
	v_add_co_u32_e32 v252, vcc, s21, v250
	s_nop 1
	v_addc_co_u32_e32 v253, vcc, 0, v251, vcc
	global_load_dword v247, v[252:253], off offset:3072
	s_mul_hi_i32 s21, s20, 0x3e0f83e1
	s_lshr_b32 s27, s21, 31
	s_ashr_i32 s21, s21, 3
	s_add_i32 s21, s21, s27
	s_mul_i32 s27, s21, 33
	s_sub_i32 s20, s20, s27
	s_mulk_i32 s20, 0xfc
	v_add_u32_e32 v198, s20, v194
	v_add_u32_e32 v223, 16, v198
	v_cmp_gt_u32_e64 s[56:57], s97, v198
	v_cmp_gt_u32_e64 s[52:53], s97, v223
	s_lshl_b32 s20, s21, 13
	v_cndmask_b32_e64 v132, 0, v198, s[56:57]
	v_cndmask_b32_e64 v136, 0, v223, s[52:53]
	v_add_u32_e32 v132, s20, v132
	v_add_u32_e32 v136, s20, v136
	v_ashrrev_i32_e32 v133, 31, v132
	v_ashrrev_i32_e32 v137, 31, v136
	v_lshlrev_b64 v[132:133], 6, v[132:133]
	v_lshlrev_b64 v[136:137], 6, v[136:137]
	v_lshl_add_u64 v[132:133], v[146:147], 0, v[132:133]
	v_lshl_add_u64 v[136:137], v[146:147], 0, v[136:137]
	flat_load_dwordx4 v[132:135], v[132:133]
	v_add_u32_e32 v227, 32, v198
	flat_load_dwordx4 v[136:139], v[136:137]
	v_add_u32_e32 v226, 48, v198
	v_cmp_gt_u32_e64 s[54:55], s97, v227
	v_add_u32_e32 v225, 64, v198
	v_cmp_gt_u32_e64 s[50:51], s97, v226
	v_cndmask_b32_e64 v152, 0, v227, s[54:55]
	v_cmp_gt_u32_e64 s[48:49], s97, v225
	v_cndmask_b32_e64 v153, 0, v226, s[50:51]
	v_add_u32_e32 v152, s20, v152
	v_cndmask_b32_e64 v155, 0, v225, s[48:49]
	v_add_u32_e32 v154, s20, v153
	v_ashrrev_i32_e32 v153, 31, v152
	v_add_u32_e32 v156, s20, v155
	v_ashrrev_i32_e32 v155, 31, v154
	v_lshlrev_b64 v[152:153], 6, v[152:153]
	v_lshlrev_b64 v[154:155], 6, v[154:155]
	v_add_u32_e32 v224, 0x50, v198
	v_cmp_gt_u32_e64 s[46:47], s97, v224
	s_mov_b32 s44, 0x358637bd
	v_add_u32_e32 v222, 0x60, v198
	v_add_u32_e32 v199, 0x70, v198
	v_cndmask_b32_e64 v157, 0, v224, s[46:47]
	v_mov_b64_e32 v[188:189], s[44:45]
	v_cmp_gt_u32_e64 s[44:45], s97, v222
	v_cmp_gt_u32_e32 vcc, s97, v199
	v_add_u32_e32 v158, s20, v157
	v_ashrrev_i32_e32 v157, 31, v156
	v_cndmask_b32_e64 v159, 0, v222, s[44:45]
	v_cndmask_b32_e32 v161, 0, v199, vcc
	v_lshlrev_b64 v[156:157], 6, v[156:157]
	s_mov_b32 s90, 0x3a800000
	v_add_u32_e32 v160, s20, v159
	v_add_u32_e32 v162, s20, v161
	v_ashrrev_i32_e32 v159, 31, v158
	v_ashrrev_i32_e32 v161, 31, v160
	v_ashrrev_i32_e32 v163, 31, v162
	v_lshlrev_b64 v[158:159], 6, v[158:159]
	v_lshlrev_b64 v[160:161], 6, v[160:161]
	v_lshlrev_b64 v[162:163], 6, v[162:163]
	s_waitcnt vmcnt(0) lgkmcnt(0)
	v_add_f32_e32 v174, v133, v132
	v_add_f32_e32 v175, v134, v135
	v_add_f32_e32 v133, v174, v175
	v_add_f32_e32 v174, v137, v136
	v_add_f32_e32 v175, v138, v139
	v_add_f32_e32 v132, v174, v175
	v_lshl_add_u64 v[136:137], v[146:147], 0, v[152:153]
	v_lshl_add_u64 v[138:139], v[146:147], 0, v[154:155]
	flat_load_dwordx4 v[190:193], v[136:137]
	flat_load_dwordx4 v[228:231], v[138:139]
	ds_bpermute_b32 v135, v195, v133
	ds_bpermute_b32 v134, v195, v132
	v_lshl_add_u64 v[136:137], v[146:147], 0, v[156:157]
	v_lshl_add_u64 v[138:139], v[146:147], 0, v[158:159]
	v_lshl_add_u64 v[152:153], v[146:147], 0, v[160:161]
	v_lshl_add_u64 v[154:155], v[146:147], 0, v[162:163]
	s_waitcnt lgkmcnt(0)
	v_pk_add_f32 v[132:133], v[132:133], v[134:135]
	ds_bpermute_b32 v135, v196, v133
	ds_bpermute_b32 v134, v196, v132
	s_waitcnt lgkmcnt(0)
	v_pk_add_f32 v[132:133], v[132:133], v[134:135]
	s_nop 0
	v_pk_fma_f32 v[156:157], v[132:133], s[90:91], v[188:189] op_sel_hi:[1,0,0]
	s_nop 0
	v_mul_f32_e32 v132, 0x4b800000, v157
	v_cmp_gt_f32_e64 s[58:59], s29, v157
	s_nop 1
	v_cndmask_b32_e64 v132, v157, v132, s[58:59]
	v_rsq_f32_e32 v157, v132
	flat_load_dwordx4 v[232:235], v[136:137]
	flat_load_dwordx4 v[236:239], v[138:139]
	s_nop 0
	flat_load_dwordx4 v[136:139], v[152:153]
	flat_load_dwordx4 v[132:135], v[154:155]
	v_mul_f32_e32 v152, 0x45800000, v157
	v_cndmask_b32_e64 v153, v157, v152, s[58:59]
	v_mul_f32_e32 v157, v122, v153
	v_cndmask_b32_e64 v153, 0, v153, s[56:57]
	v_mul_legacy_f32 v122, v126, v153
	v_mul_legacy_f32 v152, v108, v153
	v_mul_f32_e32 v108, v109, v153
	v_mul_f32_e32 v109, 0x4b800000, v156
	v_cmp_gt_f32_e64 s[58:59], s29, v156
	v_cndmask_b32_e64 v109, v156, v109, s[58:59]
	v_rsq_f32_e32 v109, v109
	v_mul_legacy_f32 v182, v128, v153
	v_cndmask_b32_e64 v128, 0, v108, s[56:57]
	v_mul_legacy_f32 v160, v130, v153
	v_mul_legacy_f32 v130, v124, v153
	v_mul_legacy_f32 v124, v110, v153
	v_mul_legacy_f32 v110, v111, v153
	v_mul_f32_e32 v108, 0x45800000, v109
	v_cndmask_b32_e64 v108, v109, v108, s[58:59]
	v_cndmask_b32_e64 v108, 0, v108, s[52:53]
	v_mul_legacy_f32 v187, v116, v108
	v_mul_legacy_f32 v181, v117, v108
	v_mul_legacy_f32 v175, v118, v108
	v_cndmask_b32_e64 v162, 0, v157, s[56:57]
	v_mul_legacy_f32 v157, v119, v108
	v_mul_legacy_f32 v119, v112, v108
	v_mul_legacy_f32 v117, v113, v108
	v_mul_legacy_f32 v186, v104, v108
	v_mul_legacy_f32 v113, v114, v108
	v_mul_f32_e32 v109, v115, v108
	v_mul_legacy_f32 v180, v105, v108
	v_mul_legacy_f32 v174, v106, v108
	v_mul_legacy_f32 v156, v107, v108
	v_mul_legacy_f32 v118, v92, v108
	s_waitcnt vmcnt(0)
; __device__ __forceinline__ float bperm_f(int src_lane, float v) { return __builtin_bit_cast(float, __builtin_amdgcn_ds_bpermute(src_lane << 2, __builtin_bit_cast(int, v))); }
;     __device__ __forceinline__ void operator()(Acc& acc, const Unit& u, int wr, int wc, int fr, int fq) const {
;     ...
;           for (int q = 0; q < 8; ++q) {
;             const int t = tbase + 16 * q; const bool ok = (t >= 0) && (t < SEQ);
;             float sq = (pq[q][0] + pq[q][1]) + (pq[q][2] + pq[q][3]); sq += bperm_f(ln ^ 16, sq); sq += bperm_f(ln ^ 32, sq);
;             const float rs = rsqrtf(sq * (1.0f / DM) + EPS);
; #pragma unroll
;             for (int bj = 0; bj < 2; ++bj)
; #pragma unroll
;                 for (int n = 0; n < 2; ++n)
; #pragma unroll
;                     for (int i = 0; i < 4; ++i) { const float v = acc[q >> 2][bj][q & 3][n][i]; acc[q >> 2][bj][q & 3][n][i] = ok ? v * rs : 0.f; }
;           }
	v_add_f32_e32 v114, v191, v190
	v_add_f32_e32 v115, v192, v193
	v_add_f32_e32 v105, v114, v115
	v_add_f32_e32 v114, v229, v228
	v_add_f32_e32 v115, v230, v231
	v_add_f32_e32 v104, v114, v115
	ds_bpermute_b32 v115, v195, v105
	ds_bpermute_b32 v114, v195, v104
	v_mul_legacy_f32 v116, v93, v108
	s_waitcnt lgkmcnt(0)
	v_pk_add_f32 v[104:105], v[104:105], v[114:115]
	ds_bpermute_b32 v107, v196, v105
	ds_bpermute_b32 v106, v196, v104
	v_mul_f32_e32 v155, v120, v153
	v_mul_legacy_f32 v178, v121, v153
	s_waitcnt lgkmcnt(0)
	v_pk_add_f32 v[92:93], v[104:105], v[106:107]
	v_mul_legacy_f32 v176, v129, v153
	v_pk_fma_f32 v[92:93], v[92:93], s[90:91], v[188:189] op_sel_hi:[1,0,0]
	v_mul_legacy_f32 v154, v131, v153
	v_mul_legacy_f32 v126, v125, v153
	v_mul_legacy_f32 v120, v127, v153
	v_cndmask_b32_e64 v184, 0, v155, s[56:57]
	v_mul_legacy_f32 v158, v123, v153
	v_mul_f32_e32 v104, 0x4b800000, v93
	v_cmp_gt_f32_e64 s[56:57], s29, v93
	v_mul_legacy_f32 v112, v94, v108
	v_cndmask_b32_e64 v93, v93, v104, s[56:57]
	v_rsq_f32_e32 v93, v93
	v_mul_legacy_f32 v108, v95, v108
	v_cndmask_b32_e64 v109, 0, v109, s[52:53]
	v_mul_f32_e32 v94, 0x45800000, v93
	v_cndmask_b32_e64 v111, v93, v94, s[56:57]
	v_mul_f32_e32 v93, v100, v111
	v_cndmask_b32_e64 v111, 0, v111, s[54:55]
	v_mul_legacy_f32 v100, v76, v111
	v_mul_f32_e32 v76, v77, v111
	v_mul_f32_e32 v77, 0x4b800000, v92
	v_cmp_gt_f32_e64 s[52:53], s29, v92
	v_cndmask_b32_e64 v115, 0, v93, s[54:55]
	v_cndmask_b32_e64 v77, v92, v77, s[52:53]
	v_mul_legacy_f32 v107, v101, v111
	v_rsq_f32_e32 v77, v77
	v_mul_legacy_f32 v105, v102, v111
	v_mul_legacy_f32 v103, v103, v111
	v_mul_f32_e32 v93, v96, v111
	v_cndmask_b32_e64 v96, 0, v76, s[54:55]
	v_mul_legacy_f32 v94, v78, v111
	v_mul_legacy_f32 v92, v79, v111
	v_mul_f32_e32 v76, 0x45800000, v77
	v_cndmask_b32_e64 v101, 0, v93, s[54:55]
	v_cndmask_b32_e64 v76, v77, v76, s[52:53]
	v_mul_legacy_f32 v97, v97, v111
	v_mul_legacy_f32 v114, v88, v111
	v_mul_legacy_f32 v95, v98, v111
	v_mul_f32_e32 v93, v99, v111
	v_mul_legacy_f32 v106, v89, v111
	v_cndmask_b32_e64 v76, 0, v76, s[50:51]
	v_mul_legacy_f32 v99, v84, v76
	v_mul_legacy_f32 v104, v90, v111
	v_mul_f32_e32 v88, v91, v111
	v_mul_legacy_f32 v91, v85, v76
	v_mul_legacy_f32 v89, v86, v76
	v_mul_legacy_f32 v87, v87, v76
	v_mul_legacy_f32 v85, v80, v76
	v_mul_legacy_f32 v81, v81, v76
	v_mul_legacy_f32 v98, v72, v76
	v_mul_legacy_f32 v79, v82, v76
	v_mul_f32_e32 v77, v83, v76
	v_mul_legacy_f32 v90, v73, v76
	v_add_f32_e32 v82, v233, v232
	v_add_f32_e32 v83, v234, v235
	v_add_f32_e32 v73, v82, v83
	v_add_f32_e32 v82, v237, v236
	v_add_f32_e32 v83, v238, v239
	v_add_f32_e32 v72, v82, v83
	ds_bpermute_b32 v83, v195, v73
	ds_bpermute_b32 v82, v195, v72
	v_cndmask_b32_e64 v102, 0, v88, s[54:55]
	v_mul_legacy_f32 v88, v74, v76
	s_waitcnt lgkmcnt(0)
	v_pk_add_f32 v[72:73], v[72:73], v[82:83]
	v_mul_legacy_f32 v86, v75, v76
	ds_bpermute_b32 v75, v196, v73
	ds_bpermute_b32 v74, v196, v72
	v_mul_legacy_f32 v84, v68, v76
	v_mul_legacy_f32 v80, v69, v76
	s_waitcnt lgkmcnt(0)
	v_pk_add_f32 v[68:69], v[72:73], v[74:75]
	v_mul_f32_e32 v70, v70, v76
	v_pk_fma_f32 v[82:83], v[68:69], s[90:91], v[188:189] op_sel_hi:[1,0,0]
	v_mul_f32_e32 v68, 0x4b800000, v83
	v_cmp_gt_f32_e64 s[52:53], s29, v83
	v_mul_legacy_f32 v76, v71, v76
	v_cndmask_b32_e64 v77, 0, v77, s[50:51]
	v_cndmask_b32_e64 v68, v83, v68, s[52:53]
	v_rsq_f32_e32 v68, v68
	v_cndmask_b32_e64 v78, 0, v70, s[50:51]
	v_cmp_gt_f32_e64 s[50:51], s29, v82
	v_cndmask_b32_e64 v93, 0, v93, s[54:55]
	v_mul_f32_e32 v69, 0x45800000, v68
	v_cndmask_b32_e64 v83, v68, v69, s[52:53]
	v_cndmask_b32_e64 v83, 0, v83, s[48:49]
	v_mul_legacy_f32 v68, v44, v83
	v_mul_f32_e32 v44, v45, v83
	v_mul_f32_e32 v45, 0x4b800000, v82
	v_cndmask_b32_e64 v45, v82, v45, s[50:51]
	v_mul_legacy_f32 v191, v64, v83
	v_rsq_f32_e32 v45, v45
	v_mul_legacy_f32 v75, v65, v83
	v_mul_legacy_f32 v69, v60, v83
	v_mul_legacy_f32 v73, v66, v83
	v_mul_f32_e32 v64, v67, v83
	v_mul_legacy_f32 v67, v61, v83
	v_cndmask_b32_e64 v66, 0, v44, s[48:49]
	v_cndmask_b32_e64 v71, 0, v64, s[48:49]
	v_mul_legacy_f32 v65, v62, v83
	v_mul_legacy_f32 v64, v46, v83
	v_mul_legacy_f32 v61, v63, v83
	v_mul_legacy_f32 v60, v47, v83
	v_mul_f32_e32 v44, 0x45800000, v45
	v_cndmask_b32_e64 v44, v45, v44, s[50:51]
	v_mul_legacy_f32 v190, v56, v83
	v_mul_legacy_f32 v74, v57, v83
	v_cndmask_b32_e64 v44, 0, v44, s[46:47]
	v_mul_legacy_f32 v193, v52, v44
	v_mul_legacy_f32 v72, v58, v83
	v_mul_f32_e32 v56, v59, v83
	v_mul_legacy_f32 v59, v53, v44
	v_mul_legacy_f32 v57, v54, v44
	v_mul_legacy_f32 v55, v55, v44
	v_mul_legacy_f32 v53, v48, v44
	v_mul_legacy_f32 v49, v49, v44
	v_mul_legacy_f32 v192, v40, v44
	v_mul_legacy_f32 v47, v50, v44
	v_mul_f32_e32 v45, v51, v44
	v_mul_legacy_f32 v58, v41, v44
	v_add_f32_e32 v50, v137, v136
	v_add_f32_e32 v51, v138, v139
	v_add_f32_e32 v41, v50, v51
	v_add_f32_e32 v50, v133, v132
	v_add_f32_e32 v51, v134, v135
	v_add_f32_e32 v40, v50, v51
	ds_bpermute_b32 v51, v195, v41
	ds_bpermute_b32 v50, v195, v40
	v_cndmask_b32_e64 v70, 0, v56, s[48:49]
	v_mul_legacy_f32 v56, v42, v44
	s_waitcnt lgkmcnt(0)
	v_pk_add_f32 v[40:41], v[40:41], v[50:51]
	v_mul_legacy_f32 v54, v43, v44
	ds_bpermute_b32 v43, v196, v41
	ds_bpermute_b32 v42, v196, v40
	v_mul_legacy_f32 v52, v28, v44
	v_mul_legacy_f32 v48, v29, v44
	s_waitcnt lgkmcnt(0)
; __device__ __forceinline__ float bperm_f(int src_lane, float v) { return __builtin_bit_cast(float, __builtin_amdgcn_ds_bpermute(src_lane << 2, __builtin_bit_cast(int, v))); }
;     __device__ __forceinline__ void operator()(Acc& acc, const Unit& u, int wr, int wc, int fr, int fq) const {
;     ...
;           for (int q = 0; q < 8; ++q) {
;             const int t = tbase + 16 * q; const bool ok = (t >= 0) && (t < SEQ);
;             float sq = (pq[q][0] + pq[q][1]) + (pq[q][2] + pq[q][3]); sq += bperm_f(ln ^ 16, sq); sq += bperm_f(ln ^ 32, sq);
;             const float rs = rsqrtf(sq * (1.0f / DM) + EPS);
; #pragma unroll
;             for (int bj = 0; bj < 2; ++bj)
; #pragma unroll
;                 for (int n = 0; n < 2; ++n)
; #pragma unroll
;                     for (int i = 0; i < 4; ++i) { const float v = acc[q >> 2][bj][q & 3][n][i]; acc[q >> 2][bj][q & 3][n][i] = ok ? v * rs : 0.f; }
;           }
;     ...
;                 const int cg_ = ch0 + 4 * n + i, cv_ = DFF + cg_;
;                 const float g0 = cw[cg_], g1 = cw[NUP + cg_], g2 = cw[2 * NUP + cg_], gb = cb[cg_];
;                 const float v0 = cw[cv_], v1 = cw[NUP + cv_], v2 = cw[2 * NUP + cv_], vb = cb[cv_];
	v_pk_add_f32 v[28:29], v[40:41], v[42:43]
	v_pk_fma_f32 v[28:29], v[28:29], s[90:91], v[188:189] op_sel_hi:[1,0,0]
	v_mul_legacy_f32 v46, v30, v44
	v_mul_f32_e32 v40, 0x4b800000, v29
	v_cmp_gt_f32_e64 s[48:49], s29, v29
	v_mul_legacy_f32 v44, v31, v44
	v_cndmask_b32_e64 v29, v29, v40, s[48:49]
	v_rsq_f32_e32 v29, v29
	v_cndmask_b32_e64 v45, 0, v45, s[46:47]
	v_cmp_gt_f32_e64 s[46:47], s29, v28
	v_mul_f32_e32 v30, 0x45800000, v29
	v_cndmask_b32_e64 v40, v29, v30, s[48:49]
	v_mul_f32_e32 v29, v36, v40
	v_cndmask_b32_e64 v40, 0, v40, s[44:45]
	v_mul_legacy_f32 v36, v12, v40
	v_mul_f32_e32 v12, v13, v40
	v_mul_f32_e32 v13, 0x4b800000, v28
	v_cndmask_b32_e64 v133, 0, v29, s[44:45]
	v_cndmask_b32_e64 v13, v28, v13, s[46:47]
	v_mul_legacy_f32 v63, v37, v40
	v_rsq_f32_e32 v13, v13
	v_mul_legacy_f32 v43, v38, v40
	v_mul_legacy_f32 v39, v39, v40
	v_mul_f32_e32 v29, v32, v40
	v_cndmask_b32_e64 v32, 0, v12, s[44:45]
	v_mul_legacy_f32 v30, v14, v40
	v_mul_legacy_f32 v28, v15, v40
	v_mul_f32_e32 v12, 0x45800000, v13
	v_cndmask_b32_e64 v12, v13, v12, s[46:47]
	v_cndmask_b32_e32 v12, 0, v12, vcc
	v_mul_legacy_f32 v135, v20, v12
	v_mul_legacy_f32 v83, v21, v12
	v_cndmask_b32_e64 v37, 0, v29, s[44:45]
	v_mul_legacy_f32 v51, v22, v12
	v_mul_legacy_f32 v33, v33, v40
	v_mul_legacy_f32 v132, v24, v40
	v_mul_legacy_f32 v41, v23, v12
	v_mul_legacy_f32 v31, v34, v40
	v_mul_f32_e32 v29, v35, v40
	v_mul_legacy_f32 v62, v25, v40
	v_mul_legacy_f32 v35, v16, v12
	v_mul_legacy_f32 v134, v8, v12
	v_mul_legacy_f32 v34, v4, v12
	v_mul_legacy_f32 v42, v26, v40
	v_mul_f32_e32 v24, v27, v40
	v_mul_legacy_f32 v27, v17, v12
	v_mul_legacy_f32 v82, v9, v12
	v_mul_legacy_f32 v26, v5, v12
	v_mul_legacy_f32 v15, v18, v12
	v_mul_legacy_f32 v50, v10, v12
	v_mul_legacy_f32 v14, v6, v12
	v_cndmask_b32_e64 v29, 0, v29, s[44:45]
	v_cndmask_b32_e64 v38, 0, v24, s[44:45]
	v_mul_legacy_f32 v13, v19, v12
	v_mul_legacy_f32 v40, v11, v12
	v_mul_legacy_f32 v12, v7, v12
	v_lshl_or_b32 v4, s34, 7, v2
	v_ashrrev_i32_e32 v5, 31, v4
	v_lshlrev_b64 v[16:17], 2, v[4:5]
	v_lshl_add_u64 v[6:7], s[36:37], 0, v[16:17]
	s_movk_i32 s21, 0x5000
	v_add_co_u32_e32 v8, vcc, s21, v6
	s_mov_b32 s21, 0xb000
	s_nop 0
	v_addc_co_u32_e32 v9, vcc, 0, v7, vcc
	v_add_co_u32_e32 v10, vcc, s21, v6
	v_lshl_add_u64 v[16:17], s[60:61], 0, v[16:17]
	s_nop 0
	v_addc_co_u32_e32 v11, vcc, 0, v7, vcc
	v_mov_b32_e32 v139, v240
	v_mov_b32_e32 v137, v241
	v_mov_b32_e32 v136, v242
	v_mov_b32_e32 v189, v243
	v_add_co_u32_e32 v18, vcc, s97, v6
	s_mov_b32 s21, 0xd000
	s_nop 0
	v_addc_co_u32_e32 v19, vcc, 0, v7, vcc
	v_add_co_u32_e32 v22, vcc, s80, v6
	v_mov_b32_e32 v138, v244
	s_nop 0
	v_addc_co_u32_e32 v23, vcc, 0, v7, vcc
	v_add_co_u32_e32 v20, vcc, s97, v16
	s_nop 0
	s_nop 0
	v_addc_co_u32_e32 v21, vcc, 0, v17, vcc
	v_add_co_u32_e32 v24, vcc, s21, v6
	v_mov_b32_e32 v188, v245
	s_nop 0
	v_addc_co_u32_e32 v25, vcc, 0, v7, vcc
	v_mov_b32_e32 v229, v246
	v_mov_b32_e32 v228, v247
	global_load_dword v232, v[6:7], off offset:4
	global_load_dword v233, v[8:9], off offset:2052
	global_load_dword v234, v[10:11], off offset:4
	global_load_dword v235, v[16:17], off offset:4
	global_load_dword v236, v[20:21], off offset:3076
	global_load_dword v237, v[18:19], off offset:3076
	global_load_dword v238, v[22:23], off offset:1028
	global_load_dword v239, v[24:25], off offset:3076
	s_nop 0
	v_mov_b32_dpp v111, v182 row_ror:1 row_mask:0xf bank_mask:0xf
	v_mov_b32_dpp v121, v182 row_ror:2 row_mask:0xf bank_mask:0xf
	v_cndmask_b32_e64 v183, v111, 0, s[38:39]
	v_cndmask_b32_e64 v155, 0, v121, s[40:41]
	v_mov_b32_dpp v123, v184 row_ror:1 row_mask:0xf bank_mask:0xf
	v_mov_b32_dpp v125, v184 row_ror:2 row_mask:0xf bank_mask:0xf
	v_cndmask_b32_e64 v185, v123, 0, s[38:39]
	v_cndmask_b32_e64 v159, 0, v125, s[40:41]
	s_waitcnt vmcnt(13)
	v_pk_mul_f32 v[182:183], v[136:137], v[182:183]
	s_waitcnt vmcnt(12)
	v_fma_f32 v155, v139, v155, v189
	v_add_f32_e32 v155, v183, v155
	v_add_f32_e32 v155, v182, v155
	v_mul_f32_e32 v161, 0xbfb8aa3b, v155
	v_exp_f32_e32 v161, v161
	v_mov_b32_e32 v183, v136
	v_add_f32_e32 v136, 1.0, v161
	v_rcp_f32_e32 v161, v136
	s_waitcnt vmcnt(10)
	v_fma_f32 v159, v138, v159, v188
	v_mul_f32_e32 v155, v155, v161
	s_waitcnt vmcnt(9)
	v_mov_b32_e32 v136, v229
	s_waitcnt vmcnt(8)
; __device__ __forceinline__ float sigmoidf_(float x) { return __builtin_amdgcn_rcpf(1.0f + __expf(-x)); }
; template <int N> __device__ __forceinline__ float dpp_ror(float v) { return __builtin_bit_cast(float, __builtin_amdgcn_update_dpp(0, __builtin_bit_cast(int, v), 0x120 + N, 0xf, 0xf, false)); }
;     __device__ __forceinline__ void operator()(Acc& acc, const Unit& u, int wr, int wc, int fr, int fq) const {
;     ...
;                 for (int q = 0; q < 8; ++q) {
;                     float cgv = acc[q >> 2][0][q & 3][n][i], cvv = acc[q >> 2][1][q & 3][n][i];
;                     asm volatile("" : "+v"(cgv), "+v"(cvv) : "v"(chain));
;                     const float tg1 = dpp_ror<1>(cgv), tg2 = dpp_ror<2>(cgv), tv1 = dpp_ror<1>(cvv), tv2 = dpp_ror<2>(cvv);
;                     const float sg1 = fr >= 1 ? tg1 : pg1, sg2 = fr >= 2 ? tg2 : pg2, sv1 = fr >= 1 ? tv1 : pv1, sv2 = fr >= 2 ? tv2 : pv2;
;                     const float gg = gb + g0 * sg2 + g1 * sg1 + g2 * cgv;
;                     const float vv = vb + v0 * sv2 + v1 * sv1 + v2 * cvv;
;                     chain = gg * sigmoidf_(gg) * vv; acc[q >> 2][0][q & 3][n][i] = chain;
;                     pg1 = tg1; pg2 = tg2; pv1 = tv1; pv2 = tv2;
;                 }
	v_pk_mul_f32 v[184:185], v[228:229], v[184:185]
	v_mov_b32_e32 v182, v228
	v_add_f32_e32 v159, v185, v159
	v_add_f32_e32 v159, v184, v159
	v_mul_f32_e32 v184, v159, v155
	v_mov_b32_dpp v129, v187 row_ror:2 row_mask:0xf bank_mask:0xf
	v_mov_b32_dpp v153, v186 row_ror:2 row_mask:0xf bank_mask:0xf
	v_mov_b32_dpp v127, v187 row_ror:1 row_mask:0xf bank_mask:0xf
	v_mov_b32_dpp v131, v186 row_ror:1 row_mask:0xf bank_mask:0xf
	v_cndmask_b32_e64 v231, v121, v129, s[40:41]
	v_cndmask_b32_e64 v230, v125, v153, s[40:41]
	v_cndmask_b32_e64 v229, v127, v111, s[38:39]
	v_cndmask_b32_e64 v228, v131, v123, s[38:39]
	v_pk_fma_f32 v[230:231], v[138:139], v[230:231], v[188:189]
	v_pk_fma_f32 v[228:229], v[136:137], v[228:229], v[230:231]
	v_pk_fma_f32 v[186:187], v[182:183], v[186:187], v[228:229]
	v_mul_f32_e32 v111, 0xbfb8aa3b, v187
	v_exp_f32_e32 v111, v111
	s_nop 0
	v_add_f32_e32 v111, 1.0, v111
	v_rcp_f32_e32 v111, v111
	s_nop 0
	v_mul_f32_e32 v111, v187, v111
	v_mul_f32_e32 v185, v186, v111
	v_mov_b32_dpp v123, v115 row_ror:2 row_mask:0xf bank_mask:0xf
	v_mov_b32_dpp v155, v114 row_ror:2 row_mask:0xf bank_mask:0xf
	v_mov_b32_dpp v121, v115 row_ror:1 row_mask:0xf bank_mask:0xf
	v_mov_b32_dpp v125, v114 row_ror:1 row_mask:0xf bank_mask:0xf
	v_cndmask_b32_e64 v229, v129, v123, s[40:41]
	v_cndmask_b32_e64 v228, v153, v155, s[40:41]
	v_cndmask_b32_e64 v187, v121, v127, s[38:39]
	v_cndmask_b32_e64 v186, v125, v131, s[38:39]
	v_pk_fma_f32 v[228:229], v[138:139], v[228:229], v[188:189]
	v_pk_fma_f32 v[186:187], v[136:137], v[186:187], v[228:229]
	v_pk_fma_f32 v[114:115], v[182:183], v[114:115], v[186:187]
	v_mul_f32_e32 v111, 0xbfb8aa3b, v115
	v_exp_f32_e32 v111, v111
	s_nop 0
	v_add_f32_e32 v111, 1.0, v111
	v_rcp_f32_e32 v111, v111
	s_nop 0
	v_mul_f32_e32 v111, v115, v111
	v_mul_f32_e32 v186, v114, v111
	v_mov_b32_dpp v129, v99 row_ror:2 row_mask:0xf bank_mask:0xf
	v_mov_b32_dpp v153, v98 row_ror:2 row_mask:0xf bank_mask:0xf
	v_mov_b32_dpp v127, v99 row_ror:1 row_mask:0xf bank_mask:0xf
	v_mov_b32_dpp v131, v98 row_ror:1 row_mask:0xf bank_mask:0xf
	v_cndmask_b32_e64 v229, v123, v129, s[40:41]
	v_cndmask_b32_e64 v228, v155, v153, s[40:41]
	v_cndmask_b32_e64 v115, v127, v121, s[38:39]
	v_cndmask_b32_e64 v114, v131, v125, s[38:39]
	v_pk_fma_f32 v[228:229], v[138:139], v[228:229], v[188:189]
	v_pk_fma_f32 v[114:115], v[136:137], v[114:115], v[228:229]
	v_pk_fma_f32 v[98:99], v[182:183], v[98:99], v[114:115]
	v_mul_f32_e32 v111, 0xbfb8aa3b, v99
	v_exp_f32_e32 v111, v111
	s_nop 0
	v_add_f32_e32 v111, 1.0, v111
	v_rcp_f32_e32 v111, v111
	s_nop 0
	v_mul_f32_e32 v99, v99, v111
	v_mul_f32_e32 v187, v98, v99
	v_mov_b32_dpp v123, v191 row_ror:2 row_mask:0xf bank_mask:0xf
	v_mov_b32_dpp v155, v190 row_ror:2 row_mask:0xf bank_mask:0xf
	v_mov_b32_dpp v121, v191 row_ror:1 row_mask:0xf bank_mask:0xf
	v_mov_b32_dpp v125, v190 row_ror:1 row_mask:0xf bank_mask:0xf
	v_cndmask_b32_e64 v115, v129, v123, s[40:41]
	v_cndmask_b32_e64 v114, v153, v155, s[40:41]
	v_cndmask_b32_e64 v99, v121, v127, s[38:39]
	v_cndmask_b32_e64 v98, v125, v131, s[38:39]
	v_pk_fma_f32 v[114:115], v[138:139], v[114:115], v[188:189]
	v_pk_fma_f32 v[98:99], v[136:137], v[98:99], v[114:115]
	v_pk_fma_f32 v[98:99], v[182:183], v[190:191], v[98:99]
	v_mul_f32_e32 v111, 0xbfb8aa3b, v99
	v_exp_f32_e32 v111, v111
	s_nop 0
	v_add_f32_e32 v111, 1.0, v111
	v_rcp_f32_e32 v111, v111
	s_nop 0
	v_mul_f32_e32 v99, v99, v111
	v_mul_f32_e32 v190, v98, v99
	v_mov_b32_dpp v129, v193 row_ror:2 row_mask:0xf bank_mask:0xf
	v_mov_b32_dpp v153, v192 row_ror:2 row_mask:0xf bank_mask:0xf
	v_mov_b32_dpp v127, v193 row_ror:1 row_mask:0xf bank_mask:0xf
	v_mov_b32_dpp v131, v192 row_ror:1 row_mask:0xf bank_mask:0xf
	v_cndmask_b32_e64 v115, v123, v129, s[40:41]
	v_cndmask_b32_e64 v114, v155, v153, s[40:41]
	v_cndmask_b32_e64 v99, v127, v121, s[38:39]
	v_cndmask_b32_e64 v98, v131, v125, s[38:39]
	v_pk_fma_f32 v[114:115], v[138:139], v[114:115], v[188:189]
	v_pk_fma_f32 v[98:99], v[136:137], v[98:99], v[114:115]
	v_pk_fma_f32 v[98:99], v[182:183], v[192:193], v[98:99]
	v_mul_f32_e32 v111, 0xbfb8aa3b, v99
	v_exp_f32_e32 v111, v111
	s_nop 0
	v_add_f32_e32 v111, 1.0, v111
	v_rcp_f32_e32 v111, v111
	s_nop 0
	v_mul_f32_e32 v99, v99, v111
	v_mul_f32_e32 v191, v98, v99
	v_mov_b32_dpp v123, v133 row_ror:2 row_mask:0xf bank_mask:0xf
	v_mov_b32_dpp v155, v132 row_ror:2 row_mask:0xf bank_mask:0xf
	v_mov_b32_dpp v121, v133 row_ror:1 row_mask:0xf bank_mask:0xf
	v_mov_b32_dpp v125, v132 row_ror:1 row_mask:0xf bank_mask:0xf
	v_cndmask_b32_e64 v115, v129, v123, s[40:41]
	v_cndmask_b32_e64 v114, v153, v155, s[40:41]
	v_cndmask_b32_e64 v99, v121, v127, s[38:39]
	v_cndmask_b32_e64 v98, v125, v131, s[38:39]
	v_pk_fma_f32 v[114:115], v[138:139], v[114:115], v[188:189]
	v_pk_fma_f32 v[98:99], v[136:137], v[98:99], v[114:115]
	v_pk_fma_f32 v[98:99], v[182:183], v[132:133], v[98:99]
	v_mul_f32_e32 v111, 0xbfb8aa3b, v99
	v_exp_f32_e32 v111, v111
	s_nop 0
	v_add_f32_e32 v111, 1.0, v111
	v_rcp_f32_e32 v111, v111
	s_nop 0
	v_mul_f32_e32 v99, v99, v111
	v_mul_f32_e32 v192, v98, v99
	v_mov_b32_dpp v114, v135 row_ror:1 row_mask:0xf bank_mask:0xf
	v_mov_b32_dpp v115, v135 row_ror:2 row_mask:0xf bank_mask:0xf
	v_mov_b32_dpp v129, v134 row_ror:2 row_mask:0xf bank_mask:0xf
	v_mov_b32_dpp v127, v134 row_ror:1 row_mask:0xf bank_mask:0xf
	v_cndmask_b32_e64 v99, v114, v121, s[38:39]
	v_cndmask_b32_e64 v115, v123, v115, s[40:41]
	v_cndmask_b32_e64 v114, v155, v129, s[40:41]
	v_cndmask_b32_e64 v98, v127, v125, s[38:39]
	v_pk_fma_f32 v[114:115], v[138:139], v[114:115], v[188:189]
	s_nop 0
	v_pk_fma_f32 v[98:99], v[136:137], v[98:99], v[114:115]
	s_nop 0
	v_pk_fma_f32 v[98:99], v[182:183], v[134:135], v[98:99]
	s_nop 0
	v_mul_f32_e32 v111, 0xbfb8aa3b, v99
	v_exp_f32_e32 v111, v111
	s_nop 0
	v_add_f32_e32 v111, 1.0, v111
	v_rcp_f32_e32 v111, v111
	s_nop 0
	v_mul_f32_e32 v99, v99, v111
	v_mul_f32_e32 v136, v98, v99
	s_waitcnt vmcnt(0)
; __device__ __forceinline__ float sigmoidf_(float x) { return __builtin_amdgcn_rcpf(1.0f + __expf(-x)); }
; template <int N> __device__ __forceinline__ float dpp_ror(float v) { return __builtin_bit_cast(float, __builtin_amdgcn_update_dpp(0, __builtin_bit_cast(int, v), 0x120 + N, 0xf, 0xf, false)); }
;     __device__ __forceinline__ void operator()(Acc& acc, const Unit& u, int wr, int wc, int fr, int fq) const {
;     ...
;                 const float g0 = cw[cg_], g1 = cw[NUP + cg_], g2 = cw[2 * NUP + cg_], gb = cb[cg_];
;                 const float v0 = cw[cv_], v1 = cw[NUP + cv_], v2 = cw[2 * NUP + cv_], vb = cb[cv_];
;                 float pg1 = 0.f, pg2 = 0.f, pv1 = 0.f, pv2 = 0.f;
; #pragma unroll
;                 for (int q = 0; q < 8; ++q) {
;                     float cgv = acc[q >> 2][0][q & 3][n][i], cvv = acc[q >> 2][1][q & 3][n][i];
;                     asm volatile("" : "+v"(cgv), "+v"(cvv) : "v"(chain));
;                     const float tg1 = dpp_ror<1>(cgv), tg2 = dpp_ror<2>(cgv), tv1 = dpp_ror<1>(cvv), tv2 = dpp_ror<2>(cvv);
;                     const float sg1 = fr >= 1 ? tg1 : pg1, sg2 = fr >= 2 ? tg2 : pg2, sv1 = fr >= 1 ? tv1 : pv1, sv2 = fr >= 2 ? tv2 : pv2;
;                     const float gg = gb + g0 * sg2 + g1 * sg1 + g2 * cgv;
;                     const float vv = vb + v0 * sv2 + v1 * sv1 + v2 * cvv;
;                     chain = gg * sigmoidf_(gg) * vv; acc[q >> 2][0][q & 3][n][i] = chain;
;                     pg1 = tg1; pg2 = tg2; pv1 = tv1; pv2 = tv2;
;                 }
	v_mov_b32_e32 v115, v232
	v_mov_b32_e32 v99, v233
	v_mov_b32_e32 v98, v234
	v_mov_b32_e32 v133, v235
	v_mov_b32_e32 v132, v236
	v_mov_b32_e32 v114, v237
	v_mov_b32_e32 v139, v238
	v_mov_b32_e32 v138, v239
	global_load_dword v240, v[6:7], off offset:8
	global_load_dword v241, v[8:9], off offset:2056
	global_load_dword v242, v[10:11], off offset:8
	global_load_dword v243, v[16:17], off offset:8
	global_load_dword v244, v[20:21], off offset:3080
	global_load_dword v245, v[18:19], off offset:3080
	global_load_dword v246, v[22:23], off offset:1032
	global_load_dword v247, v[24:25], off offset:3080
	v_mov_b32_dpp v111, v176 row_ror:1 row_mask:0xf bank_mask:0xf
	v_mov_b32_dpp v121, v176 row_ror:2 row_mask:0xf bank_mask:0xf
	v_cndmask_b32_e64 v177, v111, 0, s[38:39]
	v_cndmask_b32_e64 v134, 0, v121, s[40:41]
	v_mov_b32_dpp v123, v178 row_ror:1 row_mask:0xf bank_mask:0xf
	v_cndmask_b32_e64 v179, v123, 0, s[38:39]
	v_mov_b32_dpp v125, v178 row_ror:2 row_mask:0xf bank_mask:0xf
	v_cndmask_b32_e64 v137, 0, v125, s[40:41]
	s_nop 0
	v_fma_f32 v155, v115, v134, v133
	v_pk_mul_f32 v[134:135], v[98:99], v[176:177]
	s_nop 0
	v_fma_f32 v137, v114, v137, v132
	v_add_f32_e32 v135, v135, v155
	v_add_f32_e32 v155, v134, v135
	v_mul_f32_e32 v134, 0xbfb8aa3b, v155
	v_exp_f32_e32 v159, v134
	v_mov_b32_e32 v135, v98
	s_nop 0
	v_pk_mul_f32 v[176:177], v[138:139], v[178:179]
	v_mov_b32_e32 v134, v138
	v_add_f32_e32 v98, 1.0, v159
	v_rcp_f32_e32 v138, v98
	v_add_f32_e32 v137, v177, v137
	v_add_f32_e32 v137, v176, v137
	v_mov_b32_e32 v98, v139
	v_mul_f32_e32 v138, v155, v138
	v_mul_f32_e32 v137, v137, v138
	v_mov_b32_dpp v129, v181 row_ror:2 row_mask:0xf bank_mask:0xf
	v_mov_b32_dpp v153, v180 row_ror:2 row_mask:0xf bank_mask:0xf
	v_mov_b32_dpp v127, v181 row_ror:1 row_mask:0xf bank_mask:0xf
	v_mov_b32_dpp v131, v180 row_ror:1 row_mask:0xf bank_mask:0xf
	v_cndmask_b32_e64 v177, v121, v129, s[40:41]
	v_cndmask_b32_e64 v176, v125, v153, s[40:41]
	v_cndmask_b32_e64 v139, v127, v111, s[38:39]
	v_cndmask_b32_e64 v138, v131, v123, s[38:39]
	v_pk_fma_f32 v[176:177], v[114:115], v[176:177], v[132:133]
	v_pk_fma_f32 v[138:139], v[98:99], v[138:139], v[176:177]
	v_pk_fma_f32 v[138:139], v[134:135], v[180:181], v[138:139]
	v_mul_f32_e32 v111, 0xbfb8aa3b, v139
	v_exp_f32_e32 v111, v111
	s_nop 0
	v_add_f32_e32 v111, 1.0, v111
	v_rcp_f32_e32 v111, v111
	s_nop 0
	v_mul_f32_e32 v111, v139, v111
	v_mul_f32_e32 v138, v138, v111
	v_mov_b32_dpp v123, v107 row_ror:2 row_mask:0xf bank_mask:0xf
	v_mov_b32_dpp v155, v106 row_ror:2 row_mask:0xf bank_mask:0xf
	v_mov_b32_dpp v121, v107 row_ror:1 row_mask:0xf bank_mask:0xf
	v_mov_b32_dpp v125, v106 row_ror:1 row_mask:0xf bank_mask:0xf
	v_cndmask_b32_e64 v179, v129, v123, s[40:41]
	v_cndmask_b32_e64 v178, v153, v155, s[40:41]
	v_cndmask_b32_e64 v177, v121, v127, s[38:39]
	v_cndmask_b32_e64 v176, v125, v131, s[38:39]
	v_pk_fma_f32 v[178:179], v[114:115], v[178:179], v[132:133]
	v_pk_fma_f32 v[176:177], v[98:99], v[176:177], v[178:179]
	v_pk_fma_f32 v[106:107], v[134:135], v[106:107], v[176:177]
	v_mul_f32_e32 v111, 0xbfb8aa3b, v107
	v_exp_f32_e32 v111, v111
	s_nop 0
	v_add_f32_e32 v111, 1.0, v111
	v_rcp_f32_e32 v111, v111
	s_nop 0
	v_mul_f32_e32 v107, v107, v111
	v_mul_f32_e32 v106, v106, v107
	v_mov_b32_dpp v129, v91 row_ror:2 row_mask:0xf bank_mask:0xf
	v_mov_b32_dpp v139, v90 row_ror:2 row_mask:0xf bank_mask:0xf
	v_mov_b32_dpp v127, v91 row_ror:1 row_mask:0xf bank_mask:0xf
	v_mov_b32_dpp v131, v90 row_ror:1 row_mask:0xf bank_mask:0xf
	v_cndmask_b32_e64 v179, v123, v129, s[40:41]
	v_cndmask_b32_e64 v178, v155, v139, s[40:41]
	v_cndmask_b32_e64 v177, v127, v121, s[38:39]
	v_cndmask_b32_e64 v176, v131, v125, s[38:39]
	v_pk_fma_f32 v[178:179], v[114:115], v[178:179], v[132:133]
	v_pk_fma_f32 v[176:177], v[98:99], v[176:177], v[178:179]
	v_pk_fma_f32 v[90:91], v[134:135], v[90:91], v[176:177]
	v_mul_f32_e32 v107, 0xbfb8aa3b, v91
	v_exp_f32_e32 v107, v107
	s_nop 0
	v_add_f32_e32 v107, 1.0, v107
	v_rcp_f32_e32 v107, v107
	s_nop 0
	v_mul_f32_e32 v91, v91, v107
	v_mul_f32_e32 v90, v90, v91
	v_mov_b32_dpp v121, v75 row_ror:2 row_mask:0xf bank_mask:0xf
	v_mov_b32_dpp v125, v74 row_ror:2 row_mask:0xf bank_mask:0xf
	v_mov_b32_dpp v111, v75 row_ror:1 row_mask:0xf bank_mask:0xf
	v_mov_b32_dpp v123, v74 row_ror:1 row_mask:0xf bank_mask:0xf
	v_cndmask_b32_e64 v179, v129, v121, s[40:41]
	v_cndmask_b32_e64 v178, v139, v125, s[40:41]
	v_cndmask_b32_e64 v177, v111, v127, s[38:39]
	v_cndmask_b32_e64 v176, v123, v131, s[38:39]
	v_pk_fma_f32 v[178:179], v[114:115], v[178:179], v[132:133]
	v_pk_fma_f32 v[176:177], v[98:99], v[176:177], v[178:179]
	v_pk_fma_f32 v[74:75], v[134:135], v[74:75], v[176:177]
	v_mul_f32_e32 v91, 0xbfb8aa3b, v75
	v_exp_f32_e32 v91, v91
	s_nop 0
	v_add_f32_e32 v91, 1.0, v91
	v_rcp_f32_e32 v91, v91
	s_nop 0
	v_mul_f32_e32 v75, v75, v91
	v_mul_f32_e32 v91, v74, v75
	v_mov_b32_dpp v129, v59 row_ror:2 row_mask:0xf bank_mask:0xf
	v_mov_b32_dpp v139, v58 row_ror:2 row_mask:0xf bank_mask:0xf
	v_mov_b32_dpp v127, v59 row_ror:1 row_mask:0xf bank_mask:0xf
	v_mov_b32_dpp v131, v58 row_ror:1 row_mask:0xf bank_mask:0xf
	v_cndmask_b32_e64 v177, v121, v129, s[40:41]
	v_cndmask_b32_e64 v176, v125, v139, s[40:41]
	v_cndmask_b32_e64 v75, v127, v111, s[38:39]
	v_cndmask_b32_e64 v74, v131, v123, s[38:39]
	v_pk_fma_f32 v[176:177], v[114:115], v[176:177], v[132:133]
	v_pk_fma_f32 v[74:75], v[98:99], v[74:75], v[176:177]
	v_pk_fma_f32 v[58:59], v[134:135], v[58:59], v[74:75]
	v_mul_f32_e32 v74, 0xbfb8aa3b, v59
	v_exp_f32_e32 v74, v74
	s_nop 0
	v_add_f32_e32 v74, 1.0, v74
	v_rcp_f32_e32 v74, v74
	s_nop 0
	v_mul_f32_e32 v59, v59, v74
	v_mul_f32_e32 v107, v58, v59
; __device__ __forceinline__ float sigmoidf_(float x) { return __builtin_amdgcn_rcpf(1.0f + __expf(-x)); }
; template <int N> __device__ __forceinline__ float dpp_ror(float v) { return __builtin_bit_cast(float, __builtin_amdgcn_update_dpp(0, __builtin_bit_cast(int, v), 0x120 + N, 0xf, 0xf, false)); }
;     __device__ __forceinline__ void operator()(Acc& acc, const Unit& u, int wr, int wc, int fr, int fq) const {
;     ...
;                 const float g0 = cw[cg_], g1 = cw[NUP + cg_], g2 = cw[2 * NUP + cg_], gb = cb[cg_];
;                 const float v0 = cw[cv_], v1 = cw[NUP + cv_], v2 = cw[2 * NUP + cv_], vb = cb[cv_];
;                 float pg1 = 0.f, pg2 = 0.f, pv1 = 0.f, pv2 = 0.f;
; #pragma unroll
;                 for (int q = 0; q < 8; ++q) {
;                     float cgv = acc[q >> 2][0][q & 3][n][i], cvv = acc[q >> 2][1][q & 3][n][i];
;                     asm volatile("" : "+v"(cgv), "+v"(cvv) : "v"(chain));
;                     const float tg1 = dpp_ror<1>(cgv), tg2 = dpp_ror<2>(cgv), tv1 = dpp_ror<1>(cvv), tv2 = dpp_ror<2>(cvv);
;                     const float sg1 = fr >= 1 ? tg1 : pg1, sg2 = fr >= 2 ? tg2 : pg2, sv1 = fr >= 1 ? tv1 : pv1, sv2 = fr >= 2 ? tv2 : pv2;
;                     const float gg = gb + g0 * sg2 + g1 * sg1 + g2 * cgv;
;                     const float vv = vb + v0 * sv2 + v1 * sv1 + v2 * cvv;
;                     chain = gg * sigmoidf_(gg) * vv; acc[q >> 2][0][q & 3][n][i] = chain;
;                     pg1 = tg1; pg2 = tg2; pv1 = tv1; pv2 = tv2;
;                 }
	v_mov_b32_dpp v121, v63 row_ror:2 row_mask:0xf bank_mask:0xf
	v_mov_b32_dpp v125, v62 row_ror:2 row_mask:0xf bank_mask:0xf
	v_mov_b32_dpp v111, v63 row_ror:1 row_mask:0xf bank_mask:0xf
	v_mov_b32_dpp v123, v62 row_ror:1 row_mask:0xf bank_mask:0xf
	v_cndmask_b32_e64 v75, v129, v121, s[40:41]
	v_cndmask_b32_e64 v74, v139, v125, s[40:41]
	v_cndmask_b32_e64 v59, v111, v127, s[38:39]
	v_cndmask_b32_e64 v58, v123, v131, s[38:39]
	v_pk_fma_f32 v[74:75], v[114:115], v[74:75], v[132:133]
	v_pk_fma_f32 v[58:59], v[98:99], v[58:59], v[74:75]
	v_pk_fma_f32 v[58:59], v[134:135], v[62:63], v[58:59]
	v_mul_f32_e32 v62, 0xbfb8aa3b, v59
	v_exp_f32_e32 v62, v62
	s_nop 0
	v_add_f32_e32 v62, 1.0, v62
	v_rcp_f32_e32 v62, v62
	s_nop 0
	v_mul_f32_e32 v59, v59, v62
	v_mul_f32_e32 v139, v58, v59
	v_mov_b32_dpp v63, v83 row_ror:1 row_mask:0xf bank_mask:0xf
	v_mov_b32_dpp v74, v83 row_ror:2 row_mask:0xf bank_mask:0xf
	v_mov_b32_dpp v127, v82 row_ror:2 row_mask:0xf bank_mask:0xf
	v_mov_b32_dpp v75, v82 row_ror:1 row_mask:0xf bank_mask:0xf
	v_cndmask_b32_e64 v59, v63, v111, s[38:39]
	v_cndmask_b32_e64 v63, v121, v74, s[40:41]
	v_cndmask_b32_e64 v62, v125, v127, s[40:41]
	v_cndmask_b32_e64 v58, v75, v123, s[38:39]
	v_pk_fma_f32 v[62:63], v[114:115], v[62:63], v[132:133]
	s_nop 0
	v_pk_fma_f32 v[58:59], v[98:99], v[58:59], v[62:63]
	s_nop 0
	v_pk_fma_f32 v[58:59], v[134:135], v[82:83], v[58:59]
	s_nop 0
	v_mul_f32_e32 v62, 0xbfb8aa3b, v59
	v_exp_f32_e32 v62, v62
	s_nop 0
	v_add_f32_e32 v62, 1.0, v62
	v_rcp_f32_e32 v62, v62
	s_nop 0
	v_mul_f32_e32 v59, v59, v62
	v_mul_f32_e32 v98, v58, v59
	s_waitcnt vmcnt(0)
	v_mov_b32_e32 v63, v240
	v_mov_b32_e32 v59, v241
	v_mov_b32_e32 v58, v242
	v_mov_b32_e32 v75, v243
	v_mov_b32_e32 v74, v244
	v_mov_b32_e32 v62, v245
	v_mov_b32_e32 v115, v246
	v_mov_b32_e32 v114, v247
	global_load_dword v232, v[6:7], off offset:12
	global_load_dword v233, v[8:9], off offset:2060
	global_load_dword v234, v[10:11], off offset:12
	global_load_dword v235, v[16:17], off offset:12
	global_load_dword v236, v[20:21], off offset:3084
	global_load_dword v237, v[18:19], off offset:3084
	global_load_dword v238, v[22:23], off offset:1036
	global_load_dword v239, v[24:25], off offset:3084
	v_mov_b32_dpp v111, v160 row_ror:1 row_mask:0xf bank_mask:0xf
	v_mov_b32_dpp v121, v160 row_ror:2 row_mask:0xf bank_mask:0xf
	v_cndmask_b32_e64 v161, v111, 0, s[38:39]
	v_cndmask_b32_e64 v82, 0, v121, s[40:41]
	v_mov_b32_dpp v123, v162 row_ror:1 row_mask:0xf bank_mask:0xf
	v_cndmask_b32_e64 v163, v123, 0, s[38:39]
	v_mov_b32_dpp v125, v162 row_ror:2 row_mask:0xf bank_mask:0xf
	v_cndmask_b32_e64 v99, 0, v125, s[40:41]
	s_nop 0
	v_fma_f32 v132, v63, v82, v75
	v_pk_mul_f32 v[82:83], v[58:59], v[160:161]
	s_nop 0
	v_fma_f32 v99, v62, v99, v74
	v_add_f32_e32 v83, v83, v132
	v_add_f32_e32 v135, v82, v83
	v_mul_f32_e32 v82, 0xbfb8aa3b, v135
	v_exp_f32_e32 v153, v82
	v_mov_b32_e32 v83, v58
	s_nop 0
	v_pk_mul_f32 v[132:133], v[114:115], v[162:163]
	v_mov_b32_e32 v82, v114
	v_add_f32_e32 v58, 1.0, v153
	v_rcp_f32_e32 v114, v58
	v_add_f32_e32 v99, v133, v99
	v_add_f32_e32 v99, v132, v99
	v_mov_b32_e32 v58, v115
	v_mul_f32_e32 v114, v135, v114
	v_mul_f32_e32 v99, v99, v114
	v_mov_b32_dpp v129, v175 row_ror:2 row_mask:0xf bank_mask:0xf
	v_mov_b32_dpp v134, v174 row_ror:2 row_mask:0xf bank_mask:0xf
	v_mov_b32_dpp v127, v175 row_ror:1 row_mask:0xf bank_mask:0xf
	v_mov_b32_dpp v131, v174 row_ror:1 row_mask:0xf bank_mask:0xf
	v_cndmask_b32_e64 v133, v121, v129, s[40:41]
	v_cndmask_b32_e64 v132, v125, v134, s[40:41]
	v_cndmask_b32_e64 v115, v127, v111, s[38:39]
	v_cndmask_b32_e64 v114, v131, v123, s[38:39]
	v_pk_fma_f32 v[132:133], v[62:63], v[132:133], v[74:75]
	v_pk_fma_f32 v[114:115], v[58:59], v[114:115], v[132:133]
	v_pk_fma_f32 v[114:115], v[82:83], v[174:175], v[114:115]
	v_mul_f32_e32 v111, 0xbfb8aa3b, v115
	v_exp_f32_e32 v111, v111
	s_nop 0
	v_add_f32_e32 v111, 1.0, v111
	v_rcp_f32_e32 v111, v111
	s_nop 0
	v_mul_f32_e32 v111, v115, v111
	v_mul_f32_e32 v114, v114, v111
	v_mov_b32_dpp v123, v105 row_ror:2 row_mask:0xf bank_mask:0xf
	v_mov_b32_dpp v153, v104 row_ror:2 row_mask:0xf bank_mask:0xf
	v_mov_b32_dpp v121, v105 row_ror:1 row_mask:0xf bank_mask:0xf
	v_mov_b32_dpp v125, v104 row_ror:1 row_mask:0xf bank_mask:0xf
	v_cndmask_b32_e64 v135, v129, v123, s[40:41]
	v_cndmask_b32_e64 v134, v134, v153, s[40:41]
	v_cndmask_b32_e64 v133, v121, v127, s[38:39]
	v_cndmask_b32_e64 v132, v125, v131, s[38:39]
	v_pk_fma_f32 v[134:135], v[62:63], v[134:135], v[74:75]
	v_pk_fma_f32 v[132:133], v[58:59], v[132:133], v[134:135]
	v_pk_fma_f32 v[104:105], v[82:83], v[104:105], v[132:133]
	v_mul_f32_e32 v111, 0xbfb8aa3b, v105
	v_exp_f32_e32 v111, v111
	s_nop 0
	v_add_f32_e32 v111, 1.0, v111
	v_rcp_f32_e32 v111, v111
	s_nop 0
	v_mul_f32_e32 v105, v105, v111
	v_mul_f32_e32 v104, v104, v105
	v_mov_b32_dpp v127, v89 row_ror:2 row_mask:0xf bank_mask:0xf
	v_mov_b32_dpp v131, v88 row_ror:2 row_mask:0xf bank_mask:0xf
	v_mov_b32_dpp v115, v89 row_ror:1 row_mask:0xf bank_mask:0xf
	v_mov_b32_dpp v129, v88 row_ror:1 row_mask:0xf bank_mask:0xf
	v_cndmask_b32_e64 v135, v123, v127, s[40:41]
	v_cndmask_b32_e64 v134, v153, v131, s[40:41]
	v_cndmask_b32_e64 v133, v115, v121, s[38:39]
	v_cndmask_b32_e64 v132, v129, v125, s[38:39]
	v_pk_fma_f32 v[134:135], v[62:63], v[134:135], v[74:75]
	v_pk_fma_f32 v[132:133], v[58:59], v[132:133], v[134:135]
	v_pk_fma_f32 v[88:89], v[82:83], v[88:89], v[132:133]
	v_mul_f32_e32 v105, 0xbfb8aa3b, v89
	v_exp_f32_e32 v105, v105
	s_nop 0
	v_add_f32_e32 v105, 1.0, v105
	v_rcp_f32_e32 v105, v105
	s_nop 0
	v_mul_f32_e32 v89, v89, v105
	v_mul_f32_e32 v88, v88, v89
; __device__ __forceinline__ float sigmoidf_(float x) { return __builtin_amdgcn_rcpf(1.0f + __expf(-x)); }
; template <int N> __device__ __forceinline__ float dpp_ror(float v) { return __builtin_bit_cast(float, __builtin_amdgcn_update_dpp(0, __builtin_bit_cast(int, v), 0x120 + N, 0xf, 0xf, false)); }
;     __device__ __forceinline__ void operator()(Acc& acc, const Unit& u, int wr, int wc, int fr, int fq) const {
;     ...
;                 const float g0 = cw[cg_], g1 = cw[NUP + cg_], g2 = cw[2 * NUP + cg_], gb = cb[cg_];
;                 const float v0 = cw[cv_], v1 = cw[NUP + cv_], v2 = cw[2 * NUP + cv_], vb = cb[cv_];
;                 float pg1 = 0.f, pg2 = 0.f, pv1 = 0.f, pv2 = 0.f;
; #pragma unroll
;                 for (int q = 0; q < 8; ++q) {
;                     float cgv = acc[q >> 2][0][q & 3][n][i], cvv = acc[q >> 2][1][q & 3][n][i];
;                     asm volatile("" : "+v"(cgv), "+v"(cvv) : "v"(chain));
;                     const float tg1 = dpp_ror<1>(cgv), tg2 = dpp_ror<2>(cgv), tv1 = dpp_ror<1>(cvv), tv2 = dpp_ror<2>(cvv);
;                     const float sg1 = fr >= 1 ? tg1 : pg1, sg2 = fr >= 2 ? tg2 : pg2, sv1 = fr >= 1 ? tv1 : pv1, sv2 = fr >= 2 ? tv2 : pv2;
;                     const float gg = gb + g0 * sg2 + g1 * sg1 + g2 * cgv;
;                     const float vv = vb + v0 * sv2 + v1 * sv1 + v2 * cvv;
;                     chain = gg * sigmoidf_(gg) * vv; acc[q >> 2][0][q & 3][n][i] = chain;
;                     pg1 = tg1; pg2 = tg2; pv1 = tv1; pv2 = tv2;
;                 }
	v_mov_b32_dpp v121, v73 row_ror:2 row_mask:0xf bank_mask:0xf
	v_mov_b32_dpp v125, v72 row_ror:2 row_mask:0xf bank_mask:0xf
	v_mov_b32_dpp v111, v73 row_ror:1 row_mask:0xf bank_mask:0xf
	v_mov_b32_dpp v123, v72 row_ror:1 row_mask:0xf bank_mask:0xf
	v_cndmask_b32_e64 v135, v127, v121, s[40:41]
	v_cndmask_b32_e64 v134, v131, v125, s[40:41]
	v_cndmask_b32_e64 v133, v111, v115, s[38:39]
	v_cndmask_b32_e64 v132, v123, v129, s[38:39]
	v_pk_fma_f32 v[134:135], v[62:63], v[134:135], v[74:75]
	v_pk_fma_f32 v[132:133], v[58:59], v[132:133], v[134:135]
	v_pk_fma_f32 v[72:73], v[82:83], v[72:73], v[132:133]
	v_mul_f32_e32 v89, 0xbfb8aa3b, v73
	v_exp_f32_e32 v89, v89
	s_nop 0
	v_add_f32_e32 v89, 1.0, v89
	v_rcp_f32_e32 v89, v89
	s_nop 0
	v_mul_f32_e32 v73, v73, v89
	v_mul_f32_e32 v72, v72, v73
	v_mov_b32_dpp v115, v57 row_ror:2 row_mask:0xf bank_mask:0xf
	v_mov_b32_dpp v129, v56 row_ror:2 row_mask:0xf bank_mask:0xf
	v_mov_b32_dpp v105, v57 row_ror:1 row_mask:0xf bank_mask:0xf
	v_mov_b32_dpp v127, v56 row_ror:1 row_mask:0xf bank_mask:0xf
	v_cndmask_b32_e64 v135, v121, v115, s[40:41]
	v_cndmask_b32_e64 v134, v125, v129, s[40:41]
	v_cndmask_b32_e64 v133, v105, v111, s[38:39]
	v_cndmask_b32_e64 v132, v127, v123, s[38:39]
	v_pk_fma_f32 v[134:135], v[62:63], v[134:135], v[74:75]
	v_pk_fma_f32 v[132:133], v[58:59], v[132:133], v[134:135]
	v_pk_fma_f32 v[56:57], v[82:83], v[56:57], v[132:133]
	v_mul_f32_e32 v73, 0xbfb8aa3b, v57
	v_exp_f32_e32 v73, v73
	s_nop 0
	v_add_f32_e32 v73, 1.0, v73
	v_rcp_f32_e32 v73, v73
	s_nop 0
	v_mul_f32_e32 v57, v57, v73
	v_mul_f32_e32 v73, v56, v57
	v_mov_b32_dpp v121, v43 row_ror:2 row_mask:0xf bank_mask:0xf
	v_mov_b32_dpp v125, v42 row_ror:2 row_mask:0xf bank_mask:0xf
	v_mov_b32_dpp v111, v43 row_ror:1 row_mask:0xf bank_mask:0xf
	v_mov_b32_dpp v123, v42 row_ror:1 row_mask:0xf bank_mask:0xf
	v_cndmask_b32_e64 v133, v115, v121, s[40:41]
	v_cndmask_b32_e64 v132, v129, v125, s[40:41]
	v_cndmask_b32_e64 v57, v111, v105, s[38:39]
	v_cndmask_b32_e64 v56, v123, v127, s[38:39]
	v_pk_fma_f32 v[132:133], v[62:63], v[132:133], v[74:75]
	v_pk_fma_f32 v[56:57], v[58:59], v[56:57], v[132:133]
	v_pk_fma_f32 v[42:43], v[82:83], v[42:43], v[56:57]
	v_mul_f32_e32 v56, 0xbfb8aa3b, v43
	v_exp_f32_e32 v56, v56
	s_nop 0
	v_add_f32_e32 v56, 1.0, v56
	v_rcp_f32_e32 v56, v56
	s_nop 0
	v_mul_f32_e32 v43, v43, v56
	v_mul_f32_e32 v89, v42, v43
	v_mov_b32_dpp v57, v51 row_ror:1 row_mask:0xf bank_mask:0xf
	v_mov_b32_dpp v105, v51 row_ror:2 row_mask:0xf bank_mask:0xf
	v_mov_b32_dpp v127, v50 row_ror:2 row_mask:0xf bank_mask:0xf
	v_mov_b32_dpp v115, v50 row_ror:1 row_mask:0xf bank_mask:0xf
	v_cndmask_b32_e64 v43, v57, v111, s[38:39]
	v_cndmask_b32_e64 v57, v121, v105, s[40:41]
	v_cndmask_b32_e64 v56, v125, v127, s[40:41]
	v_cndmask_b32_e64 v42, v115, v123, s[38:39]
	v_pk_fma_f32 v[56:57], v[62:63], v[56:57], v[74:75]
	s_nop 0
	v_pk_fma_f32 v[42:43], v[58:59], v[42:43], v[56:57]
	s_nop 0
	v_pk_fma_f32 v[42:43], v[82:83], v[50:51], v[42:43]
	s_nop 0
	v_mul_f32_e32 v50, 0xbfb8aa3b, v43
	v_exp_f32_e32 v50, v50
	s_nop 0
	v_add_f32_e32 v50, 1.0, v50
	v_rcp_f32_e32 v50, v50
	s_nop 0
	v_mul_f32_e32 v43, v43, v50
	v_mul_f32_e32 v62, v42, v43
	s_waitcnt vmcnt(0)
	v_mov_b32_e32 v51, v232
	v_mov_b32_e32 v43, v233
	v_mov_b32_e32 v42, v234
	v_mov_b32_e32 v57, v235
	v_mov_b32_e32 v56, v236
	v_mov_b32_e32 v50, v237
	v_mov_b32_e32 v75, v238
	v_mov_b32_e32 v74, v239
	global_load_dword v240, v[6:7], off offset:16
	global_load_dword v241, v[8:9], off offset:2064
	global_load_dword v242, v[10:11], off offset:16
	global_load_dword v243, v[16:17], off offset:16
	global_load_dword v244, v[20:21], off offset:3088
	global_load_dword v245, v[18:19], off offset:3088
	global_load_dword v246, v[22:23], off offset:1040
	global_load_dword v247, v[24:25], off offset:3088
	v_mov_b32_dpp v105, v154 row_ror:1 row_mask:0xf bank_mask:0xf
	v_mov_b32_dpp v111, v154 row_ror:2 row_mask:0xf bank_mask:0xf
	v_cndmask_b32_e64 v155, v105, 0, s[38:39]
	v_cndmask_b32_e64 v58, 0, v111, s[40:41]
	v_mov_b32_dpp v115, v158 row_ror:1 row_mask:0xf bank_mask:0xf
	v_cndmask_b32_e64 v159, v115, 0, s[38:39]
	v_mov_b32_dpp v121, v158 row_ror:2 row_mask:0xf bank_mask:0xf
	v_cndmask_b32_e64 v63, 0, v121, s[40:41]
	s_nop 0
	v_fma_f32 v82, v51, v58, v57
	v_pk_mul_f32 v[58:59], v[42:43], v[154:155]
	s_nop 0
	v_fma_f32 v63, v50, v63, v56
	v_add_f32_e32 v59, v59, v82
	v_add_f32_e32 v131, v58, v59
	v_mul_f32_e32 v58, 0xbfb8aa3b, v131
	v_exp_f32_e32 v132, v58
	v_mov_b32_e32 v59, v42
	s_nop 0
	v_pk_mul_f32 v[82:83], v[74:75], v[158:159]
	v_mov_b32_e32 v58, v74
	v_add_f32_e32 v42, 1.0, v132
	v_rcp_f32_e32 v74, v42
	v_add_f32_e32 v63, v83, v63
	v_add_f32_e32 v63, v82, v63
	v_mov_b32_e32 v42, v75
	v_mul_f32_e32 v74, v131, v74
	v_mul_f32_e32 v63, v63, v74
	v_mov_b32_dpp v125, v157 row_ror:2 row_mask:0xf bank_mask:0xf
	v_mov_b32_dpp v129, v156 row_ror:2 row_mask:0xf bank_mask:0xf
	v_mov_b32_dpp v123, v157 row_ror:1 row_mask:0xf bank_mask:0xf
	v_mov_b32_dpp v127, v156 row_ror:1 row_mask:0xf bank_mask:0xf
	v_cndmask_b32_e64 v83, v111, v125, s[40:41]
	v_cndmask_b32_e64 v82, v121, v129, s[40:41]
	v_cndmask_b32_e64 v75, v123, v105, s[38:39]
	v_cndmask_b32_e64 v74, v127, v115, s[38:39]
	v_pk_fma_f32 v[82:83], v[50:51], v[82:83], v[56:57]
	v_pk_fma_f32 v[74:75], v[42:43], v[74:75], v[82:83]
	v_pk_fma_f32 v[74:75], v[58:59], v[156:157], v[74:75]
	v_mul_f32_e32 v82, 0xbfb8aa3b, v75
	v_exp_f32_e32 v82, v82
	s_nop 0
	v_add_f32_e32 v82, 1.0, v82
	v_rcp_f32_e32 v82, v82
	s_nop 0
	v_mul_f32_e32 v75, v75, v82
	v_mul_f32_e32 v74, v74, v75
	v_mov_b32_dpp v111, v103 row_ror:2 row_mask:0xf bank_mask:0xf
	v_mov_b32_dpp v121, v102 row_ror:2 row_mask:0xf bank_mask:0xf
; __device__ __forceinline__ float sigmoidf_(float x) { return __builtin_amdgcn_rcpf(1.0f + __expf(-x)); }
; template <int N> __device__ __forceinline__ float dpp_ror(float v) { return __builtin_bit_cast(float, __builtin_amdgcn_update_dpp(0, __builtin_bit_cast(int, v), 0x120 + N, 0xf, 0xf, false)); }
;     __device__ __forceinline__ void operator()(Acc& acc, const Unit& u, int wr, int wc, int fr, int fq) const {
;     ...
;                 for (int q = 0; q < 8; ++q) {
;                     float cgv = acc[q >> 2][0][q & 3][n][i], cvv = acc[q >> 2][1][q & 3][n][i];
;                     asm volatile("" : "+v"(cgv), "+v"(cvv) : "v"(chain));
;                     const float tg1 = dpp_ror<1>(cgv), tg2 = dpp_ror<2>(cgv), tv1 = dpp_ror<1>(cvv), tv2 = dpp_ror<2>(cvv);
;                     const float sg1 = fr >= 1 ? tg1 : pg1, sg2 = fr >= 2 ? tg2 : pg2, sv1 = fr >= 1 ? tv1 : pv1, sv2 = fr >= 2 ? tv2 : pv2;
;                     const float gg = gb + g0 * sg2 + g1 * sg1 + g2 * cgv;
;                     const float vv = vb + v0 * sv2 + v1 * sv1 + v2 * cvv;
;                     chain = gg * sigmoidf_(gg) * vv; acc[q >> 2][0][q & 3][n][i] = chain;
;                     pg1 = tg1; pg2 = tg2; pv1 = tv1; pv2 = tv2;
;                 }
	v_mov_b32_dpp v105, v103 row_ror:1 row_mask:0xf bank_mask:0xf
	v_mov_b32_dpp v115, v102 row_ror:1 row_mask:0xf bank_mask:0xf
	v_cndmask_b32_e64 v133, v125, v111, s[40:41]
	v_cndmask_b32_e64 v132, v129, v121, s[40:41]
	v_cndmask_b32_e64 v83, v105, v123, s[38:39]
	v_cndmask_b32_e64 v82, v115, v127, s[38:39]
	v_pk_fma_f32 v[132:133], v[50:51], v[132:133], v[56:57]
	v_pk_fma_f32 v[82:83], v[42:43], v[82:83], v[132:133]
	v_pk_fma_f32 v[82:83], v[58:59], v[102:103], v[82:83]
	v_mul_f32_e32 v75, 0xbfb8aa3b, v83
	v_exp_f32_e32 v75, v75
	s_nop 0
	v_add_f32_e32 v75, 1.0, v75
	v_rcp_f32_e32 v75, v75
	s_nop 0
	v_mul_f32_e32 v75, v83, v75
	v_mul_f32_e32 v75, v82, v75
	v_mov_b32_dpp v125, v87 row_ror:2 row_mask:0xf bank_mask:0xf
	v_mov_b32_dpp v129, v86 row_ror:2 row_mask:0xf bank_mask:0xf
	v_mov_b32_dpp v123, v87 row_ror:1 row_mask:0xf bank_mask:0xf
	v_mov_b32_dpp v127, v86 row_ror:1 row_mask:0xf bank_mask:0xf
	v_cndmask_b32_e64 v103, v111, v125, s[40:41]
	v_cndmask_b32_e64 v102, v121, v129, s[40:41]
	v_cndmask_b32_e64 v83, v123, v105, s[38:39]
	v_cndmask_b32_e64 v82, v127, v115, s[38:39]
	v_pk_fma_f32 v[102:103], v[50:51], v[102:103], v[56:57]
	v_pk_fma_f32 v[82:83], v[42:43], v[82:83], v[102:103]
	v_pk_fma_f32 v[82:83], v[58:59], v[86:87], v[82:83]
	v_mul_f32_e32 v86, 0xbfb8aa3b, v83
	v_exp_f32_e32 v86, v86
	s_nop 0
	v_add_f32_e32 v86, 1.0, v86
	v_rcp_f32_e32 v86, v86
	s_nop 0
	v_mul_f32_e32 v83, v83, v86
	v_mul_f32_e32 v82, v82, v83
	v_mov_b32_dpp v111, v71 row_ror:2 row_mask:0xf bank_mask:0xf
	v_mov_b32_dpp v121, v70 row_ror:2 row_mask:0xf bank_mask:0xf
	v_mov_b32_dpp v105, v71 row_ror:1 row_mask:0xf bank_mask:0xf
	v_mov_b32_dpp v115, v70 row_ror:1 row_mask:0xf bank_mask:0xf
	v_cndmask_b32_e64 v103, v125, v111, s[40:41]
	v_cndmask_b32_e64 v102, v129, v121, s[40:41]
	v_cndmask_b32_e64 v87, v105, v123, s[38:39]
	v_cndmask_b32_e64 v86, v115, v127, s[38:39]
	v_pk_fma_f32 v[102:103], v[50:51], v[102:103], v[56:57]
	v_pk_fma_f32 v[86:87], v[42:43], v[86:87], v[102:103]
	v_pk_fma_f32 v[70:71], v[58:59], v[70:71], v[86:87]
	v_mul_f32_e32 v83, 0xbfb8aa3b, v71
	v_exp_f32_e32 v83, v83
	s_nop 0
	v_add_f32_e32 v83, 1.0, v83
	v_rcp_f32_e32 v83, v83
	s_nop 0
	v_mul_f32_e32 v71, v71, v83
	v_mul_f32_e32 v70, v70, v71
	v_mov_b32_dpp v125, v55 row_ror:2 row_mask:0xf bank_mask:0xf
	v_mov_b32_dpp v129, v54 row_ror:2 row_mask:0xf bank_mask:0xf
	v_mov_b32_dpp v123, v55 row_ror:1 row_mask:0xf bank_mask:0xf
	v_mov_b32_dpp v127, v54 row_ror:1 row_mask:0xf bank_mask:0xf
	v_cndmask_b32_e64 v103, v111, v125, s[40:41]
	v_cndmask_b32_e64 v102, v121, v129, s[40:41]
	v_cndmask_b32_e64 v87, v123, v105, s[38:39]
	v_cndmask_b32_e64 v86, v127, v115, s[38:39]
	v_pk_fma_f32 v[102:103], v[50:51], v[102:103], v[56:57]
	v_pk_fma_f32 v[86:87], v[42:43], v[86:87], v[102:103]
	v_pk_fma_f32 v[54:55], v[58:59], v[54:55], v[86:87]
	v_mul_f32_e32 v71, 0xbfb8aa3b, v55
	v_exp_f32_e32 v71, v71
	s_nop 0
	v_add_f32_e32 v71, 1.0, v71
	v_rcp_f32_e32 v71, v71
	s_nop 0
	v_mul_f32_e32 v55, v55, v71
	v_mul_f32_e32 v55, v54, v55
	v_mov_b32_dpp v105, v39 row_ror:2 row_mask:0xf bank_mask:0xf
	v_mov_b32_dpp v115, v38 row_ror:2 row_mask:0xf bank_mask:0xf
	v_mov_b32_dpp v83, v39 row_ror:1 row_mask:0xf bank_mask:0xf
	v_mov_b32_dpp v111, v38 row_ror:1 row_mask:0xf bank_mask:0xf
	v_cndmask_b32_e64 v103, v125, v105, s[40:41]
	v_cndmask_b32_e64 v102, v129, v115, s[40:41]
	v_cndmask_b32_e64 v87, v83, v123, s[38:39]
	v_cndmask_b32_e64 v86, v111, v127, s[38:39]
	v_pk_fma_f32 v[102:103], v[50:51], v[102:103], v[56:57]
	s_nop 0
	v_pk_fma_f32 v[86:87], v[42:43], v[86:87], v[102:103]
	v_pk_fma_f32 v[38:39], v[58:59], v[38:39], v[86:87]
	v_mul_f32_e32 v54, 0xbfb8aa3b, v39
	v_exp_f32_e32 v54, v54
	s_nop 0
	v_add_f32_e32 v54, 1.0, v54
	v_rcp_f32_e32 v54, v54
	s_nop 0
	v_mul_f32_e32 v39, v39, v54
	v_mul_f32_e32 v71, v38, v39
	v_mov_b32_dpp v86, v41 row_ror:1 row_mask:0xf bank_mask:0xf
	v_mov_b32_dpp v87, v41 row_ror:2 row_mask:0xf bank_mask:0xf
	v_mov_b32_dpp v103, v40 row_ror:2 row_mask:0xf bank_mask:0xf
	v_mov_b32_dpp v102, v40 row_ror:1 row_mask:0xf bank_mask:0xf
	v_cndmask_b32_e64 v39, v86, v83, s[38:39]
	v_cndmask_b32_e64 v87, v105, v87, s[40:41]
	v_cndmask_b32_e64 v86, v115, v103, s[40:41]
	v_cndmask_b32_e64 v38, v102, v111, s[38:39]
	v_pk_fma_f32 v[50:51], v[50:51], v[86:87], v[56:57]
	s_nop 0
	v_pk_fma_f32 v[38:39], v[42:43], v[38:39], v[50:51]
	s_nop 0
	v_pk_fma_f32 v[38:39], v[58:59], v[40:41], v[38:39]
	s_nop 0
	v_mul_f32_e32 v40, 0xbfb8aa3b, v39
	v_exp_f32_e32 v40, v40
	s_nop 0
	v_add_f32_e32 v40, 1.0, v40
	v_rcp_f32_e32 v40, v40
	s_nop 0
	v_mul_f32_e32 v39, v39, v40
	v_mul_f32_e32 v54, v38, v39
	s_waitcnt vmcnt(0)
; __device__ __forceinline__ float sigmoidf_(float x) { return __builtin_amdgcn_rcpf(1.0f + __expf(-x)); }
; template <int N> __device__ __forceinline__ float dpp_ror(float v) { return __builtin_bit_cast(float, __builtin_amdgcn_update_dpp(0, __builtin_bit_cast(int, v), 0x120 + N, 0xf, 0xf, false)); }
;     __device__ __forceinline__ void operator()(Acc& acc, const Unit& u, int wr, int wc, int fr, int fq) const {
;     ...
;                 const float g0 = cw[cg_], g1 = cw[NUP + cg_], g2 = cw[2 * NUP + cg_], gb = cb[cg_];
;                 const float v0 = cw[cv_], v1 = cw[NUP + cv_], v2 = cw[2 * NUP + cv_], vb = cb[cv_];
;                 float pg1 = 0.f, pg2 = 0.f, pv1 = 0.f, pv2 = 0.f;
; #pragma unroll
;                 for (int q = 0; q < 8; ++q) {
;                     float cgv = acc[q >> 2][0][q & 3][n][i], cvv = acc[q >> 2][1][q & 3][n][i];
;                     asm volatile("" : "+v"(cgv), "+v"(cvv) : "v"(chain));
;                     const float tg1 = dpp_ror<1>(cgv), tg2 = dpp_ror<2>(cgv), tv1 = dpp_ror<1>(cvv), tv2 = dpp_ror<2>(cvv);
;                     const float sg1 = fr >= 1 ? tg1 : pg1, sg2 = fr >= 2 ? tg2 : pg2, sv1 = fr >= 1 ? tv1 : pv1, sv2 = fr >= 2 ? tv2 : pv2;
;                     const float gg = gb + g0 * sg2 + g1 * sg1 + g2 * cgv;
;                     const float vv = vb + v0 * sv2 + v1 * sv1 + v2 * cvv;
;                     chain = gg * sigmoidf_(gg) * vv; acc[q >> 2][0][q & 3][n][i] = chain;
;                     pg1 = tg1; pg2 = tg2; pv1 = tv1; pv2 = tv2;
;                 }
	v_mov_b32_e32 v41, v240
	v_mov_b32_e32 v39, v241
	v_mov_b32_e32 v38, v242
	v_mov_b32_e32 v43, v243
	v_mov_b32_e32 v42, v244
	v_mov_b32_e32 v40, v245
	v_mov_b32_e32 v57, v246
	v_mov_b32_e32 v56, v247
	global_load_dword v232, v[6:7], off offset:20
	global_load_dword v233, v[8:9], off offset:2068
	global_load_dword v234, v[10:11], off offset:20
	global_load_dword v235, v[16:17], off offset:20
	global_load_dword v236, v[20:21], off offset:3092
	global_load_dword v237, v[18:19], off offset:3092
	global_load_dword v238, v[22:23], off offset:1044
	global_load_dword v239, v[24:25], off offset:3092
	v_mov_b32_dpp v83, v130 row_ror:1 row_mask:0xf bank_mask:0xf
	v_mov_b32_dpp v86, v130 row_ror:2 row_mask:0xf bank_mask:0xf
	v_cndmask_b32_e64 v131, v83, 0, s[38:39]
	v_cndmask_b32_e64 v50, 0, v86, s[40:41]
	v_mov_b32_dpp v87, v152 row_ror:1 row_mask:0xf bank_mask:0xf
	v_mov_b32_dpp v102, v152 row_ror:2 row_mask:0xf bank_mask:0xf
	v_cndmask_b32_e64 v153, v87, 0, s[38:39]
	v_cndmask_b32_e64 v58, 0, v102, s[40:41]
	s_nop 0
	v_fma_f32 v59, v41, v50, v43
	v_pk_mul_f32 v[50:51], v[38:39], v[130:131]
	s_nop 0
	v_fma_f32 v121, v40, v58, v42
	v_add_f32_e32 v51, v51, v59
	v_add_f32_e32 v123, v50, v51
	v_mul_f32_e32 v50, 0xbfb8aa3b, v123
	v_exp_f32_e32 v125, v50
	v_mov_b32_e32 v51, v38
	s_nop 0
	v_pk_mul_f32 v[58:59], v[56:57], v[152:153]
	v_mov_b32_e32 v50, v56
	v_add_f32_e32 v38, 1.0, v125
	v_rcp_f32_e32 v56, v38
	v_mov_b32_e32 v38, v57
	v_add_f32_e32 v57, v59, v121
	v_add_f32_e32 v57, v58, v57
	v_mul_f32_e32 v56, v123, v56
	v_mul_f32_e32 v56, v57, v56
	v_mov_b32_dpp v105, v119 row_ror:2 row_mask:0xf bank_mask:0xf
	v_mov_b32_dpp v111, v118 row_ror:1 row_mask:0xf bank_mask:0xf
	v_mov_b32_dpp v115, v118 row_ror:2 row_mask:0xf bank_mask:0xf
	v_mov_b32_dpp v103, v119 row_ror:1 row_mask:0xf bank_mask:0xf
	v_cndmask_b32_e64 v58, v111, v87, s[38:39]
	v_cndmask_b32_e64 v87, v86, v105, s[40:41]
	v_cndmask_b32_e64 v86, v102, v115, s[40:41]
	v_cndmask_b32_e64 v59, v103, v83, s[38:39]
	v_pk_fma_f32 v[86:87], v[40:41], v[86:87], v[42:43]
	v_pk_fma_f32 v[58:59], v[38:39], v[58:59], v[86:87]
	v_pk_fma_f32 v[58:59], v[50:51], v[118:119], v[58:59]
	v_mul_f32_e32 v57, 0xbfb8aa3b, v59
	v_exp_f32_e32 v57, v57
	s_nop 0
	v_add_f32_e32 v57, 1.0, v57
	v_rcp_f32_e32 v57, v57
	s_nop 0
	v_mul_f32_e32 v57, v59, v57
	v_mul_f32_e32 v57, v58, v57
	v_mov_b32_dpp v102, v101 row_ror:2 row_mask:0xf bank_mask:0xf
	v_mov_b32_dpp v119, v100 row_ror:2 row_mask:0xf bank_mask:0xf
	v_mov_b32_dpp v83, v101 row_ror:1 row_mask:0xf bank_mask:0xf
	v_mov_b32_dpp v118, v100 row_ror:1 row_mask:0xf bank_mask:0xf
	v_cndmask_b32_e64 v87, v105, v102, s[40:41]
	v_cndmask_b32_e64 v86, v115, v119, s[40:41]
	v_cndmask_b32_e64 v59, v83, v103, s[38:39]
	v_cndmask_b32_e64 v58, v118, v111, s[38:39]
	v_pk_fma_f32 v[86:87], v[40:41], v[86:87], v[42:43]
	v_pk_fma_f32 v[58:59], v[38:39], v[58:59], v[86:87]
	v_pk_fma_f32 v[58:59], v[50:51], v[100:101], v[58:59]
	v_mul_f32_e32 v86, 0xbfb8aa3b, v59
	v_exp_f32_e32 v86, v86
	s_nop 0
	v_add_f32_e32 v86, 1.0, v86
	v_rcp_f32_e32 v86, v86
	s_nop 0
	v_mul_f32_e32 v59, v59, v86
	v_mul_f32_e32 v58, v58, v59
	v_mov_b32_dpp v105, v85 row_ror:2 row_mask:0xf bank_mask:0xf
	v_mov_b32_dpp v115, v84 row_ror:2 row_mask:0xf bank_mask:0xf
	v_mov_b32_dpp v103, v85 row_ror:1 row_mask:0xf bank_mask:0xf
	v_mov_b32_dpp v111, v84 row_ror:1 row_mask:0xf bank_mask:0xf
	v_cndmask_b32_e64 v101, v102, v105, s[40:41]
	v_cndmask_b32_e64 v100, v119, v115, s[40:41]
	v_cndmask_b32_e64 v87, v103, v83, s[38:39]
	v_cndmask_b32_e64 v86, v111, v118, s[38:39]
	v_pk_fma_f32 v[100:101], v[40:41], v[100:101], v[42:43]
	v_pk_fma_f32 v[86:87], v[38:39], v[86:87], v[100:101]
	v_pk_fma_f32 v[84:85], v[50:51], v[84:85], v[86:87]
	v_mul_f32_e32 v59, 0xbfb8aa3b, v85
	v_exp_f32_e32 v59, v59
	s_nop 0
	v_add_f32_e32 v59, 1.0, v59
	v_rcp_f32_e32 v59, v59
	s_nop 0
	v_mul_f32_e32 v59, v85, v59
	v_mul_f32_e32 v59, v84, v59
	v_mov_b32_dpp v100, v69 row_ror:2 row_mask:0xf bank_mask:0xf
	v_mov_b32_dpp v102, v68 row_ror:2 row_mask:0xf bank_mask:0xf
	v_mov_b32_dpp v83, v69 row_ror:1 row_mask:0xf bank_mask:0xf
	v_mov_b32_dpp v101, v68 row_ror:1 row_mask:0xf bank_mask:0xf
	v_cndmask_b32_e64 v87, v105, v100, s[40:41]
	v_cndmask_b32_e64 v86, v115, v102, s[40:41]
	v_cndmask_b32_e64 v85, v83, v103, s[38:39]
	v_cndmask_b32_e64 v84, v101, v111, s[38:39]
	v_pk_fma_f32 v[86:87], v[40:41], v[86:87], v[42:43]
	v_pk_fma_f32 v[84:85], v[38:39], v[84:85], v[86:87]
	v_pk_fma_f32 v[68:69], v[50:51], v[68:69], v[84:85]
	v_mul_f32_e32 v84, 0xbfb8aa3b, v69
	v_exp_f32_e32 v84, v84
	s_nop 0
	v_add_f32_e32 v84, 1.0, v84
	v_rcp_f32_e32 v84, v84
	s_nop 0
	v_mul_f32_e32 v69, v69, v84
	v_mul_f32_e32 v68, v68, v69
	v_mov_b32_dpp v105, v53 row_ror:2 row_mask:0xf bank_mask:0xf
	v_mov_b32_dpp v115, v52 row_ror:2 row_mask:0xf bank_mask:0xf
	v_mov_b32_dpp v103, v53 row_ror:1 row_mask:0xf bank_mask:0xf
	v_mov_b32_dpp v111, v52 row_ror:1 row_mask:0xf bank_mask:0xf
	v_cndmask_b32_e64 v87, v100, v105, s[40:41]
	v_cndmask_b32_e64 v86, v102, v115, s[40:41]
	v_cndmask_b32_e64 v85, v103, v83, s[38:39]
	v_cndmask_b32_e64 v84, v111, v101, s[38:39]
	v_pk_fma_f32 v[86:87], v[40:41], v[86:87], v[42:43]
	v_pk_fma_f32 v[84:85], v[38:39], v[84:85], v[86:87]
	v_pk_fma_f32 v[52:53], v[50:51], v[52:53], v[84:85]
	v_mul_f32_e32 v69, 0xbfb8aa3b, v53
	v_exp_f32_e32 v69, v69
	s_nop 0
	v_add_f32_e32 v69, 1.0, v69
	v_rcp_f32_e32 v69, v69
	s_nop 0
	v_mul_f32_e32 v53, v53, v69
	v_mul_f32_e32 v52, v52, v53
	v_mov_b32_dpp v100, v37 row_ror:2 row_mask:0xf bank_mask:0xf
	v_mov_b32_dpp v102, v36 row_ror:2 row_mask:0xf bank_mask:0xf
	v_mov_b32_dpp v83, v37 row_ror:1 row_mask:0xf bank_mask:0xf
	v_mov_b32_dpp v101, v36 row_ror:1 row_mask:0xf bank_mask:0xf
	v_cndmask_b32_e64 v87, v105, v100, s[40:41]
	v_cndmask_b32_e64 v86, v115, v102, s[40:41]
	v_cndmask_b32_e64 v85, v83, v103, s[38:39]
	v_cndmask_b32_e64 v84, v101, v111, s[38:39]
	v_pk_fma_f32 v[86:87], v[40:41], v[86:87], v[42:43]
	s_nop 0
	v_pk_fma_f32 v[84:85], v[38:39], v[84:85], v[86:87]
	v_pk_fma_f32 v[36:37], v[50:51], v[36:37], v[84:85]
	v_mul_f32_e32 v53, 0xbfb8aa3b, v37
	v_exp_f32_e32 v53, v53
	s_nop 0
	v_add_f32_e32 v53, 1.0, v53
	v_rcp_f32_e32 v53, v53
	s_nop 0
	v_mul_f32_e32 v37, v37, v53
	v_mul_f32_e32 v53, v36, v37
	v_mov_b32_dpp v84, v35 row_ror:2 row_mask:0xf bank_mask:0xf
	v_mov_b32_dpp v85, v34 row_ror:1 row_mask:0xf bank_mask:0xf
	v_mov_b32_dpp v86, v34 row_ror:2 row_mask:0xf bank_mask:0xf
	v_mov_b32_dpp v69, v35 row_ror:1 row_mask:0xf bank_mask:0xf
	v_cndmask_b32_e64 v36, v85, v101, s[38:39]
	v_cndmask_b32_e64 v85, v100, v84, s[40:41]
	v_cndmask_b32_e64 v84, v102, v86, s[40:41]
	v_cndmask_b32_e64 v37, v69, v83, s[38:39]
	v_pk_fma_f32 v[40:41], v[40:41], v[84:85], v[42:43]
	s_nop 0
	v_pk_fma_f32 v[36:37], v[38:39], v[36:37], v[40:41]
	s_nop 0
	v_pk_fma_f32 v[34:35], v[50:51], v[34:35], v[36:37]
	s_nop 0
	v_mul_f32_e32 v36, 0xbfb8aa3b, v35
	v_exp_f32_e32 v36, v36
	s_nop 0
	v_add_f32_e32 v36, 1.0, v36
	v_rcp_f32_e32 v36, v36
	s_nop 0
	v_mul_f32_e32 v35, v35, v36
	v_mul_f32_e32 v42, v34, v35
	s_waitcnt vmcnt(0)
; __device__ __forceinline__ float sigmoidf_(float x) { return __builtin_amdgcn_rcpf(1.0f + __expf(-x)); }
; template <int N> __device__ __forceinline__ float dpp_ror(float v) { return __builtin_bit_cast(float, __builtin_amdgcn_update_dpp(0, __builtin_bit_cast(int, v), 0x120 + N, 0xf, 0xf, false)); }
;     __device__ __forceinline__ void operator()(Acc& acc, const Unit& u, int wr, int wc, int fr, int fq) const {
;     ...
;                 const float g0 = cw[cg_], g1 = cw[NUP + cg_], g2 = cw[2 * NUP + cg_], gb = cb[cg_];
;                 const float v0 = cw[cv_], v1 = cw[NUP + cv_], v2 = cw[2 * NUP + cv_], vb = cb[cv_];
;                 float pg1 = 0.f, pg2 = 0.f, pv1 = 0.f, pv2 = 0.f;
; #pragma unroll
;                 for (int q = 0; q < 8; ++q) {
;                     float cgv = acc[q >> 2][0][q & 3][n][i], cvv = acc[q >> 2][1][q & 3][n][i];
;                     asm volatile("" : "+v"(cgv), "+v"(cvv) : "v"(chain));
;                     const float tg1 = dpp_ror<1>(cgv), tg2 = dpp_ror<2>(cgv), tv1 = dpp_ror<1>(cvv), tv2 = dpp_ror<2>(cvv);
;                     const float sg1 = fr >= 1 ? tg1 : pg1, sg2 = fr >= 2 ? tg2 : pg2, sv1 = fr >= 1 ? tv1 : pv1, sv2 = fr >= 2 ? tv2 : pv2;
;                     const float gg = gb + g0 * sg2 + g1 * sg1 + g2 * cgv;
;                     const float vv = vb + v0 * sv2 + v1 * sv1 + v2 * cvv;
;                     chain = gg * sigmoidf_(gg) * vv; acc[q >> 2][0][q & 3][n][i] = chain;
;                     pg1 = tg1; pg2 = tg2; pv1 = tv1; pv2 = tv2;
;                 }
	v_mov_b32_e32 v37, v232
	v_mov_b32_e32 v35, v233
	v_mov_b32_e32 v34, v234
	v_mov_b32_e32 v39, v235
	v_mov_b32_e32 v38, v236
	v_mov_b32_e32 v36, v237
	v_mov_b32_e32 v51, v238
	v_mov_b32_e32 v50, v239
	global_load_dword v240, v[6:7], off offset:24
	global_load_dword v241, v[8:9], off offset:2072
	global_load_dword v242, v[10:11], off offset:24
	global_load_dword v243, v[16:17], off offset:24
	global_load_dword v244, v[20:21], off offset:3096
	global_load_dword v245, v[18:19], off offset:3096
	global_load_dword v246, v[22:23], off offset:1048
	global_load_dword v247, v[24:25], off offset:3096
	v_mov_b32_dpp v69, v126 row_ror:1 row_mask:0xf bank_mask:0xf
	v_mov_b32_dpp v83, v126 row_ror:2 row_mask:0xf bank_mask:0xf
	v_cndmask_b32_e64 v127, v69, 0, s[38:39]
	v_cndmask_b32_e64 v40, 0, v83, s[40:41]
	v_mov_b32_dpp v86, v128 row_ror:1 row_mask:0xf bank_mask:0xf
	v_cndmask_b32_e64 v129, v86, 0, s[38:39]
	v_mov_b32_dpp v87, v128 row_ror:2 row_mask:0xf bank_mask:0xf
	v_cndmask_b32_e64 v43, 0, v87, s[40:41]
	s_nop 0
	v_fma_f32 v84, v37, v40, v39
	v_pk_mul_f32 v[40:41], v[34:35], v[126:127]
	s_nop 0
	v_fma_f32 v43, v36, v43, v38
	v_add_f32_e32 v41, v41, v84
	v_add_f32_e32 v105, v40, v41
	v_mul_f32_e32 v40, 0xbfb8aa3b, v105
	v_exp_f32_e32 v111, v40
	v_mov_b32_e32 v41, v34
	s_nop 0
	v_pk_mul_f32 v[84:85], v[50:51], v[128:129]
	v_mov_b32_e32 v40, v50
	v_add_f32_e32 v34, 1.0, v111
	v_rcp_f32_e32 v50, v34
	v_add_f32_e32 v43, v85, v43
	v_add_f32_e32 v43, v84, v43
	v_mov_b32_e32 v34, v51
	v_mul_f32_e32 v50, v105, v50
	v_mul_f32_e32 v43, v43, v50
	v_mov_b32_dpp v101, v117 row_ror:2 row_mask:0xf bank_mask:0xf
	v_mov_b32_dpp v103, v116 row_ror:2 row_mask:0xf bank_mask:0xf
	v_mov_b32_dpp v100, v117 row_ror:1 row_mask:0xf bank_mask:0xf
	v_mov_b32_dpp v102, v116 row_ror:1 row_mask:0xf bank_mask:0xf
	v_cndmask_b32_e64 v85, v83, v101, s[40:41]
	v_cndmask_b32_e64 v84, v87, v103, s[40:41]
	v_cndmask_b32_e64 v51, v100, v69, s[38:39]
	v_cndmask_b32_e64 v50, v102, v86, s[38:39]
	v_pk_fma_f32 v[84:85], v[36:37], v[84:85], v[38:39]
	v_pk_fma_f32 v[50:51], v[34:35], v[50:51], v[84:85]
	s_nop 0
	v_pk_fma_f32 v[50:51], v[40:41], v[116:117], v[50:51]
	s_nop 0
	v_mul_f32_e32 v69, 0xbfb8aa3b, v51
	v_exp_f32_e32 v69, v69
	s_nop 0
	v_add_f32_e32 v69, 1.0, v69
	v_rcp_f32_e32 v69, v69
	s_nop 0
	v_mul_f32_e32 v51, v51, v69
	v_mul_f32_e32 v50, v50, v51
	v_mov_b32_dpp v105, v97 row_ror:2 row_mask:0xf bank_mask:0xf
	v_mov_b32_dpp v115, v96 row_ror:2 row_mask:0xf bank_mask:0xf
	v_mov_b32_dpp v83, v97 row_ror:1 row_mask:0xf bank_mask:0xf
	v_mov_b32_dpp v111, v96 row_ror:1 row_mask:0xf bank_mask:0xf
	v_cndmask_b32_e64 v87, v101, v105, s[40:41]
	v_cndmask_b32_e64 v86, v103, v115, s[40:41]
	v_cndmask_b32_e64 v85, v83, v100, s[38:39]
	v_cndmask_b32_e64 v84, v111, v102, s[38:39]
	v_pk_fma_f32 v[86:87], v[36:37], v[86:87], v[38:39]
	v_pk_fma_f32 v[84:85], v[34:35], v[84:85], v[86:87]
	v_pk_fma_f32 v[84:85], v[40:41], v[96:97], v[84:85]
	v_mul_f32_e32 v51, 0xbfb8aa3b, v85
	v_exp_f32_e32 v51, v51
	s_nop 0
	v_add_f32_e32 v51, 1.0, v51
	v_rcp_f32_e32 v51, v51
	s_nop 0
	v_mul_f32_e32 v51, v85, v51
	v_mul_f32_e32 v51, v84, v51
	v_mov_b32_dpp v97, v81 row_ror:2 row_mask:0xf bank_mask:0xf
	v_mov_b32_dpp v101, v80 row_ror:2 row_mask:0xf bank_mask:0xf
	v_mov_b32_dpp v96, v81 row_ror:1 row_mask:0xf bank_mask:0xf
	v_mov_b32_dpp v100, v80 row_ror:1 row_mask:0xf bank_mask:0xf
	v_cndmask_b32_e64 v87, v105, v97, s[40:41]
	v_cndmask_b32_e64 v86, v115, v101, s[40:41]
	v_cndmask_b32_e64 v85, v96, v83, s[38:39]
	v_cndmask_b32_e64 v84, v100, v111, s[38:39]
	v_pk_fma_f32 v[86:87], v[36:37], v[86:87], v[38:39]
	v_pk_fma_f32 v[84:85], v[34:35], v[84:85], v[86:87]
	v_pk_fma_f32 v[80:81], v[40:41], v[80:81], v[84:85]
	v_mul_f32_e32 v69, 0xbfb8aa3b, v81
	v_exp_f32_e32 v69, v69
	s_nop 0
	v_add_f32_e32 v69, 1.0, v69
	v_rcp_f32_e32 v69, v69
	s_nop 0
	v_mul_f32_e32 v69, v81, v69
	v_mul_f32_e32 v69, v80, v69
	v_mov_b32_dpp v86, v67 row_ror:2 row_mask:0xf bank_mask:0xf
	v_mov_b32_dpp v102, v66 row_ror:2 row_mask:0xf bank_mask:0xf
	v_mov_b32_dpp v83, v67 row_ror:1 row_mask:0xf bank_mask:0xf
	v_mov_b32_dpp v87, v66 row_ror:1 row_mask:0xf bank_mask:0xf
	v_cndmask_b32_e64 v85, v97, v86, s[40:41]
	v_cndmask_b32_e64 v84, v101, v102, s[40:41]
	v_cndmask_b32_e64 v81, v83, v96, s[38:39]
	v_cndmask_b32_e64 v80, v87, v100, s[38:39]
	v_pk_fma_f32 v[84:85], v[36:37], v[84:85], v[38:39]
	v_pk_fma_f32 v[80:81], v[34:35], v[80:81], v[84:85]
	v_pk_fma_f32 v[66:67], v[40:41], v[66:67], v[80:81]
	v_mul_f32_e32 v80, 0xbfb8aa3b, v67
	v_exp_f32_e32 v80, v80
	s_nop 0
	v_add_f32_e32 v80, 1.0, v80
	v_rcp_f32_e32 v80, v80
	s_nop 0
	v_mul_f32_e32 v67, v67, v80
	v_mul_f32_e32 v66, v66, v67
	v_mov_b32_dpp v97, v49 row_ror:2 row_mask:0xf bank_mask:0xf
	v_mov_b32_dpp v101, v48 row_ror:2 row_mask:0xf bank_mask:0xf
	v_mov_b32_dpp v96, v49 row_ror:1 row_mask:0xf bank_mask:0xf
	v_mov_b32_dpp v100, v48 row_ror:1 row_mask:0xf bank_mask:0xf
	v_cndmask_b32_e64 v85, v86, v97, s[40:41]
	v_cndmask_b32_e64 v84, v102, v101, s[40:41]
	v_cndmask_b32_e64 v81, v96, v83, s[38:39]
	v_cndmask_b32_e64 v80, v100, v87, s[38:39]
	v_pk_fma_f32 v[84:85], v[36:37], v[84:85], v[38:39]
	v_pk_fma_f32 v[80:81], v[34:35], v[80:81], v[84:85]
	v_pk_fma_f32 v[48:49], v[40:41], v[48:49], v[80:81]
	v_mul_f32_e32 v67, 0xbfb8aa3b, v49
	v_exp_f32_e32 v67, v67
	s_nop 0
	v_add_f32_e32 v67, 1.0, v67
	v_rcp_f32_e32 v67, v67
	s_nop 0
	v_mul_f32_e32 v49, v49, v67
	v_mul_f32_e32 v48, v48, v49
	v_mov_b32_dpp v86, v33 row_ror:2 row_mask:0xf bank_mask:0xf
	v_mov_b32_dpp v102, v32 row_ror:2 row_mask:0xf bank_mask:0xf
	v_mov_b32_dpp v83, v33 row_ror:1 row_mask:0xf bank_mask:0xf
	v_mov_b32_dpp v87, v32 row_ror:1 row_mask:0xf bank_mask:0xf
	v_cndmask_b32_e64 v85, v97, v86, s[40:41]
	v_cndmask_b32_e64 v84, v101, v102, s[40:41]
	v_cndmask_b32_e64 v81, v83, v96, s[38:39]
	v_cndmask_b32_e64 v80, v87, v100, s[38:39]
	v_pk_fma_f32 v[84:85], v[36:37], v[84:85], v[38:39]
	s_nop 0
	v_pk_fma_f32 v[80:81], v[34:35], v[80:81], v[84:85]
	v_pk_fma_f32 v[32:33], v[40:41], v[32:33], v[80:81]
	v_mul_f32_e32 v49, 0xbfb8aa3b, v33
	v_exp_f32_e32 v49, v49
	s_nop 0
	v_add_f32_e32 v49, 1.0, v49
	v_rcp_f32_e32 v49, v49
	s_nop 0
	v_mul_f32_e32 v33, v33, v49
	v_mul_f32_e32 v49, v32, v33
	v_mov_b32_dpp v80, v27 row_ror:2 row_mask:0xf bank_mask:0xf
	v_mov_b32_dpp v81, v26 row_ror:1 row_mask:0xf bank_mask:0xf
	v_mov_b32_dpp v84, v26 row_ror:2 row_mask:0xf bank_mask:0xf
	v_mov_b32_dpp v67, v27 row_ror:1 row_mask:0xf bank_mask:0xf
	v_cndmask_b32_e64 v32, v81, v87, s[38:39]
	v_cndmask_b32_e64 v81, v86, v80, s[40:41]
	v_cndmask_b32_e64 v80, v102, v84, s[40:41]
	v_cndmask_b32_e64 v33, v67, v83, s[38:39]
	v_pk_fma_f32 v[36:37], v[36:37], v[80:81], v[38:39]
	s_nop 0
	v_pk_fma_f32 v[32:33], v[34:35], v[32:33], v[36:37]
	s_nop 0
	v_pk_fma_f32 v[26:27], v[40:41], v[26:27], v[32:33]
	s_nop 0
	v_mul_f32_e32 v32, 0xbfb8aa3b, v27
	v_exp_f32_e32 v32, v32
	s_nop 0
	v_add_f32_e32 v32, 1.0, v32
	v_rcp_f32_e32 v32, v32
	s_nop 0
	v_mul_f32_e32 v27, v27, v32
	v_mul_f32_e32 v38, v26, v27
	s_waitcnt vmcnt(0)
; __device__ __forceinline__ float sigmoidf_(float x) { return __builtin_amdgcn_rcpf(1.0f + __expf(-x)); }
; template <int N> __device__ __forceinline__ float dpp_ror(float v) { return __builtin_bit_cast(float, __builtin_amdgcn_update_dpp(0, __builtin_bit_cast(int, v), 0x120 + N, 0xf, 0xf, false)); }
;     __device__ __forceinline__ void operator()(Acc& acc, const Unit& u, int wr, int wc, int fr, int fq) const {
;     ...
;             for (int i = 0; i < 4; ++i) {
;                 const int cg_ = ch0 + 4 * n + i, cv_ = DFF + cg_;
;                 const float g0 = cw[cg_], g1 = cw[NUP + cg_], g2 = cw[2 * NUP + cg_], gb = cb[cg_];
;                 const float v0 = cw[cv_], v1 = cw[NUP + cv_], v2 = cw[2 * NUP + cv_], vb = cb[cv_];
;                 float pg1 = 0.f, pg2 = 0.f, pv1 = 0.f, pv2 = 0.f;
; #pragma unroll
;                 for (int q = 0; q < 8; ++q) {
;                     float cgv = acc[q >> 2][0][q & 3][n][i], cvv = acc[q >> 2][1][q & 3][n][i];
;                     asm volatile("" : "+v"(cgv), "+v"(cvv) : "v"(chain));
;                     const float tg1 = dpp_ror<1>(cgv), tg2 = dpp_ror<2>(cgv), tv1 = dpp_ror<1>(cvv), tv2 = dpp_ror<2>(cvv);
;                     const float sg1 = fr >= 1 ? tg1 : pg1, sg2 = fr >= 2 ? tg2 : pg2, sv1 = fr >= 1 ? tv1 : pv1, sv2 = fr >= 2 ? tv2 : pv2;
;                     const float gg = gb + g0 * sg2 + g1 * sg1 + g2 * cgv;
;                     const float vv = vb + v0 * sv2 + v1 * sv1 + v2 * cvv;
;                     chain = gg * sigmoidf_(gg) * vv; acc[q >> 2][0][q & 3][n][i] = chain;
;                     pg1 = tg1; pg2 = tg2; pv1 = tv1; pv2 = tv2;
;                 }
	v_mov_b32_e32 v33, v240
	v_mov_b32_e32 v27, v241
	v_mov_b32_e32 v26, v242
	v_mov_b32_e32 v35, v243
	v_mov_b32_e32 v34, v244
	v_mov_b32_e32 v32, v245
	v_mov_b32_e32 v41, v246
	v_mov_b32_e32 v40, v247
	global_load_dword v232, v[6:7], off offset:28
	global_load_dword v233, v[8:9], off offset:2076
	global_load_dword v234, v[10:11], off offset:28
	global_load_dword v235, v[16:17], off offset:28
	global_load_dword v236, v[18:19], off offset:3100
	global_load_dword v237, v[22:23], off offset:1052
	global_load_dword v238, v[24:25], off offset:3100
	global_load_dword v239, v[20:21], off offset:3100
	v_mov_b32_dpp v67, v122 row_ror:1 row_mask:0xf bank_mask:0xf
	v_mov_b32_dpp v83, v122 row_ror:2 row_mask:0xf bank_mask:0xf
	v_cndmask_b32_e64 v123, v67, 0, s[38:39]
	v_cndmask_b32_e64 v36, 0, v83, s[40:41]
	v_mov_b32_dpp v84, v124 row_ror:1 row_mask:0xf bank_mask:0xf
	v_cndmask_b32_e64 v125, v84, 0, s[38:39]
	v_mov_b32_dpp v85, v124 row_ror:2 row_mask:0xf bank_mask:0xf
	v_cndmask_b32_e64 v39, 0, v85, s[40:41]
	s_nop 0
	v_fma_f32 v80, v33, v36, v35
	v_pk_mul_f32 v[36:37], v[26:27], v[122:123]
	s_nop 0
	v_fma_f32 v39, v32, v39, v34
	v_add_f32_e32 v37, v37, v80
	v_add_f32_e32 v100, v36, v37
	v_mul_f32_e32 v36, 0xbfb8aa3b, v100
	v_exp_f32_e32 v101, v36
	v_mov_b32_e32 v37, v26
	s_nop 0
	v_pk_mul_f32 v[80:81], v[40:41], v[124:125]
	v_mov_b32_e32 v36, v40
	v_add_f32_e32 v26, 1.0, v101
	v_rcp_f32_e32 v40, v26
	v_add_f32_e32 v39, v81, v39
	v_add_f32_e32 v39, v80, v39
	v_mov_b32_e32 v26, v41
	v_mul_f32_e32 v40, v100, v40
	v_mul_f32_e32 v39, v39, v40
	v_mov_b32_dpp v87, v113 row_ror:2 row_mask:0xf bank_mask:0xf
	v_mov_b32_dpp v97, v112 row_ror:2 row_mask:0xf bank_mask:0xf
	v_mov_b32_dpp v86, v113 row_ror:1 row_mask:0xf bank_mask:0xf
	v_mov_b32_dpp v96, v112 row_ror:1 row_mask:0xf bank_mask:0xf
	v_cndmask_b32_e64 v81, v83, v87, s[40:41]
	v_cndmask_b32_e64 v80, v85, v97, s[40:41]
	v_cndmask_b32_e64 v41, v86, v67, s[38:39]
	v_cndmask_b32_e64 v40, v96, v84, s[38:39]
	v_pk_fma_f32 v[80:81], v[32:33], v[80:81], v[34:35]
	v_pk_fma_f32 v[40:41], v[26:27], v[40:41], v[80:81]
	s_nop 0
	v_pk_fma_f32 v[40:41], v[36:37], v[112:113], v[40:41]
	s_nop 0
	v_mul_f32_e32 v67, 0xbfb8aa3b, v41
	v_exp_f32_e32 v67, v67
	s_nop 0
	v_add_f32_e32 v67, 1.0, v67
	v_rcp_f32_e32 v67, v67
	s_nop 0
	v_mul_f32_e32 v41, v41, v67
	v_mul_f32_e32 v40, v40, v41
	v_mov_b32_dpp v100, v95 row_ror:2 row_mask:0xf bank_mask:0xf
	v_mov_b32_dpp v102, v94 row_ror:2 row_mask:0xf bank_mask:0xf
	v_mov_b32_dpp v83, v95 row_ror:1 row_mask:0xf bank_mask:0xf
	v_mov_b32_dpp v101, v94 row_ror:1 row_mask:0xf bank_mask:0xf
	v_cndmask_b32_e64 v85, v87, v100, s[40:41]
	v_cndmask_b32_e64 v84, v97, v102, s[40:41]
	v_cndmask_b32_e64 v81, v83, v86, s[38:39]
	v_cndmask_b32_e64 v80, v101, v96, s[38:39]
	v_pk_fma_f32 v[84:85], v[32:33], v[84:85], v[34:35]
	v_pk_fma_f32 v[80:81], v[26:27], v[80:81], v[84:85]
	v_pk_fma_f32 v[80:81], v[36:37], v[94:95], v[80:81]
	v_mul_f32_e32 v41, 0xbfb8aa3b, v81
	v_exp_f32_e32 v41, v41
	s_nop 0
	v_add_f32_e32 v41, 1.0, v41
	v_rcp_f32_e32 v41, v41
	s_nop 0
	v_mul_f32_e32 v41, v81, v41
	v_mul_f32_e32 v41, v80, v41
	v_mov_b32_dpp v87, v79 row_ror:2 row_mask:0xf bank_mask:0xf
	v_mov_b32_dpp v95, v78 row_ror:2 row_mask:0xf bank_mask:0xf
	v_mov_b32_dpp v86, v79 row_ror:1 row_mask:0xf bank_mask:0xf
	v_mov_b32_dpp v94, v78 row_ror:1 row_mask:0xf bank_mask:0xf
	v_cndmask_b32_e64 v85, v100, v87, s[40:41]
	v_cndmask_b32_e64 v84, v102, v95, s[40:41]
	v_cndmask_b32_e64 v81, v86, v83, s[38:39]
	v_cndmask_b32_e64 v80, v94, v101, s[38:39]
	v_pk_fma_f32 v[84:85], v[32:33], v[84:85], v[34:35]
	v_pk_fma_f32 v[80:81], v[26:27], v[80:81], v[84:85]
	v_pk_fma_f32 v[78:79], v[36:37], v[78:79], v[80:81]
	v_mul_f32_e32 v67, 0xbfb8aa3b, v79
	v_exp_f32_e32 v67, v67
	s_nop 0
	v_add_f32_e32 v67, 1.0, v67
	v_rcp_f32_e32 v67, v67
	s_nop 0
	v_mul_f32_e32 v67, v79, v67
	v_mul_f32_e32 v67, v78, v67
	v_mov_b32_dpp v84, v65 row_ror:2 row_mask:0xf bank_mask:0xf
	v_mov_b32_dpp v96, v64 row_ror:2 row_mask:0xf bank_mask:0xf
	v_mov_b32_dpp v83, v65 row_ror:1 row_mask:0xf bank_mask:0xf
	v_mov_b32_dpp v85, v64 row_ror:1 row_mask:0xf bank_mask:0xf
	v_cndmask_b32_e64 v81, v87, v84, s[40:41]
	v_cndmask_b32_e64 v80, v95, v96, s[40:41]
	v_cndmask_b32_e64 v79, v83, v86, s[38:39]
	v_cndmask_b32_e64 v78, v85, v94, s[38:39]
	v_pk_fma_f32 v[80:81], v[32:33], v[80:81], v[34:35]
	v_pk_fma_f32 v[78:79], v[26:27], v[78:79], v[80:81]
	v_pk_fma_f32 v[64:65], v[36:37], v[64:65], v[78:79]
	v_mul_f32_e32 v78, 0xbfb8aa3b, v65
	v_exp_f32_e32 v78, v78
	s_nop 0
	v_add_f32_e32 v78, 1.0, v78
	v_rcp_f32_e32 v78, v78
	s_nop 0
	v_mul_f32_e32 v65, v65, v78
	v_mul_f32_e32 v64, v64, v65
	v_mov_b32_dpp v87, v47 row_ror:2 row_mask:0xf bank_mask:0xf
	v_mov_b32_dpp v95, v46 row_ror:2 row_mask:0xf bank_mask:0xf
	v_mov_b32_dpp v86, v47 row_ror:1 row_mask:0xf bank_mask:0xf
	v_mov_b32_dpp v94, v46 row_ror:1 row_mask:0xf bank_mask:0xf
	v_cndmask_b32_e64 v81, v84, v87, s[40:41]
	v_cndmask_b32_e64 v80, v96, v95, s[40:41]
	v_cndmask_b32_e64 v79, v86, v83, s[38:39]
	v_cndmask_b32_e64 v78, v94, v85, s[38:39]
	v_pk_fma_f32 v[80:81], v[32:33], v[80:81], v[34:35]
	v_pk_fma_f32 v[78:79], v[26:27], v[78:79], v[80:81]
	v_pk_fma_f32 v[46:47], v[36:37], v[46:47], v[78:79]
	v_mul_f32_e32 v65, 0xbfb8aa3b, v47
	v_exp_f32_e32 v65, v65
	s_nop 0
	v_add_f32_e32 v65, 1.0, v65
	v_rcp_f32_e32 v65, v65
	s_nop 0
	v_mul_f32_e32 v47, v47, v65
	v_mul_f32_e32 v46, v46, v47
	v_mov_b32_dpp v84, v31 row_ror:2 row_mask:0xf bank_mask:0xf
	v_mov_b32_dpp v96, v30 row_ror:2 row_mask:0xf bank_mask:0xf
	v_mov_b32_dpp v83, v31 row_ror:1 row_mask:0xf bank_mask:0xf
	v_mov_b32_dpp v85, v30 row_ror:1 row_mask:0xf bank_mask:0xf
	v_cndmask_b32_e64 v81, v87, v84, s[40:41]
	v_cndmask_b32_e64 v80, v95, v96, s[40:41]
	v_cndmask_b32_e64 v79, v83, v86, s[38:39]
	v_cndmask_b32_e64 v78, v85, v94, s[38:39]
	v_pk_fma_f32 v[80:81], v[32:33], v[80:81], v[34:35]
	v_pk_fma_f32 v[78:79], v[26:27], v[78:79], v[80:81]
	v_pk_fma_f32 v[30:31], v[36:37], v[30:31], v[78:79]
	v_mul_f32_e32 v47, 0xbfb8aa3b, v31
	v_exp_f32_e32 v47, v47
	s_nop 0
	v_add_f32_e32 v47, 1.0, v47
	v_rcp_f32_e32 v47, v47
	s_nop 0
	v_mul_f32_e32 v31, v31, v47
	v_mul_f32_e32 v30, v30, v31
	v_mov_b32_dpp v80, v15 row_ror:2 row_mask:0xf bank_mask:0xf
	v_mov_b32_dpp v86, v14 row_ror:2 row_mask:0xf bank_mask:0xf
	v_mov_b32_dpp v65, v15 row_ror:1 row_mask:0xf bank_mask:0xf
	v_mov_b32_dpp v78, v14 row_ror:1 row_mask:0xf bank_mask:0xf
	v_cndmask_b32_e64 v81, v84, v80, s[40:41]
	v_cndmask_b32_e64 v80, v96, v86, s[40:41]
	v_cndmask_b32_e64 v79, v65, v83, s[38:39]
	v_cndmask_b32_e64 v78, v78, v85, s[38:39]
	v_pk_fma_f32 v[32:33], v[32:33], v[80:81], v[34:35]
	s_nop 0
	v_pk_fma_f32 v[26:27], v[26:27], v[78:79], v[32:33]
	s_nop 0
	v_pk_fma_f32 v[14:15], v[36:37], v[14:15], v[26:27]
	s_nop 0
	v_mul_f32_e32 v26, 0xbfb8aa3b, v15
	v_exp_f32_e32 v26, v26
	s_nop 0
	v_add_f32_e32 v26, 1.0, v26
	v_rcp_f32_e32 v26, v26
	s_nop 0
	v_mul_f32_e32 v15, v15, v26
	v_mul_f32_e32 v26, v14, v15
	s_waitcnt vmcnt(0)
; __device__ __forceinline__ unsigned pk2(float lo, float hi) { const f32x2_t v = {lo, hi}; const bf16x2_t b = __builtin_convertvector(v, bf16x2_t); return __builtin_bit_cast(unsigned, b); }
; __device__ __forceinline__ float sigmoidf_(float x) { return __builtin_amdgcn_rcpf(1.0f + __expf(-x)); }
; template <int N> __device__ __forceinline__ float dpp_ror(float v) { return __builtin_bit_cast(float, __builtin_amdgcn_update_dpp(0, __builtin_bit_cast(int, v), 0x120 + N, 0xf, 0xf, false)); }
;     __device__ __forceinline__ void operator()(Acc& acc, const Unit& u, int wr, int wc, int fr, int fq) const {
;     ...
;                 for (int q = 0; q < 8; ++q) {
;                     float cgv = acc[q >> 2][0][q & 3][n][i], cvv = acc[q >> 2][1][q & 3][n][i];
;                     asm volatile("" : "+v"(cgv), "+v"(cvv) : "v"(chain));
;                     const float tg1 = dpp_ror<1>(cgv), tg2 = dpp_ror<2>(cgv), tv1 = dpp_ror<1>(cvv), tv2 = dpp_ror<2>(cvv);
;                     const float sg1 = fr >= 1 ? tg1 : pg1, sg2 = fr >= 2 ? tg2 : pg2, sv1 = fr >= 1 ? tv1 : pv1, sv2 = fr >= 2 ? tv2 : pv2;
;                     const float gg = gb + g0 * sg2 + g1 * sg1 + g2 * cgv;
;                     const float vv = vb + v0 * sv2 + v1 * sv1 + v2 * cvv;
;                     chain = gg * sigmoidf_(gg) * vv; acc[q >> 2][0][q & 3][n][i] = chain;
;                     pg1 = tg1; pg2 = tg2; pv1 = tv1; pv2 = tv2;
;                 }
;     ...
;         for (int q = 0; q < 8; ++q) {
;             const int t = tbase + 16 * q;
;             if ((16 * q + fr >= 2) && (t < SEQ)) {
;                 const f32x4 a0 = acc[q >> 2][0][q & 3][0], a1 = acc[q >> 2][0][q & 3][1];
;                 u32x4 w; w.x = pk2(a0[0], a0[1]); w.y = pk2(a0[2], a0[3]); w.z = pk2(a1[0], a1[1]); w.w = pk2(a1[2], a1[3]);
;                 *(u32x4*)(act + (size_t)(b * SEQ + t) * DFF + ch0) = w;
	v_mov_b32_e32 v15, v232
	s_nop 0
	v_mov_b32_e32 v7, v233
	v_mov_b32_e32 v6, v234
	s_nop 0
	v_mov_b32_e32 v9, v235
	v_mov_b32_e32 v14, v236
	s_nop 0
	v_mov_b32_e32 v17, v237
	v_mov_b32_e32 v16, v238
	v_mov_b32_e32 v8, v239
	v_mov_b32_dpp v19, v120 row_ror:1 row_mask:0xf bank_mask:0xf
	v_mov_b32_dpp v22, v120 row_ror:2 row_mask:0xf bank_mask:0xf
	v_cndmask_b32_e64 v121, v19, 0, s[38:39]
	v_cndmask_b32_e64 v10, 0, v22, s[40:41]
	v_mov_b32_dpp v20, v110 row_ror:1 row_mask:0xf bank_mask:0xf
	v_mov_b32_dpp v24, v110 row_ror:2 row_mask:0xf bank_mask:0xf
	v_cndmask_b32_e64 v111, v20, 0, s[38:39]
	v_cndmask_b32_e64 v18, 0, v24, s[40:41]
	v_mov_b32_e32 v35, v3
	v_mov_b32_e32 v36, v3
	s_nop 0
	v_fma_f32 v21, v15, v10, v9
	v_pk_mul_f32 v[10:11], v[6:7], v[120:121]
	s_nop 0
	v_fma_f32 v18, v14, v18, v8
	v_add_f32_e32 v11, v11, v21
	v_add_f32_e32 v21, v10, v11
	v_pk_mul_f32 v[10:11], v[16:17], v[110:111]
	s_nop 0
	v_add_f32_e32 v11, v11, v18
	v_add_f32_e32 v10, v10, v11
	v_mul_f32_e32 v11, 0xbfb8aa3b, v21
	v_exp_f32_e32 v11, v11
	s_nop 0
	v_add_f32_e32 v11, 1.0, v11
	v_rcp_f32_e32 v11, v11
	s_nop 0
	v_mul_f32_e32 v11, v21, v11
	v_mul_f32_e32 v18, v10, v11
	v_mov_b32_e32 v11, v6
	v_mov_b32_e32 v6, v17
	v_mov_b32_dpp v27, v109 row_ror:2 row_mask:0xf bank_mask:0xf
	v_mov_b32_dpp v32, v108 row_ror:2 row_mask:0xf bank_mask:0xf
	v_mov_b32_dpp v25, v109 row_ror:1 row_mask:0xf bank_mask:0xf
	v_mov_b32_dpp v31, v108 row_ror:1 row_mask:0xf bank_mask:0xf
	v_cndmask_b32_e64 v23, v22, v27, s[40:41]
	v_cndmask_b32_e64 v22, v24, v32, s[40:41]
	v_cndmask_b32_e64 v21, v25, v19, s[38:39]
	v_cndmask_b32_e64 v20, v31, v20, s[38:39]
	v_pk_fma_f32 v[22:23], v[14:15], v[22:23], v[8:9]
	v_mov_b32_e32 v10, v16
	v_pk_fma_f32 v[16:17], v[6:7], v[20:21], v[22:23]
	v_pk_fma_f32 v[16:17], v[10:11], v[108:109], v[16:17]
	s_nop 0
	v_mul_f32_e32 v19, 0xbfb8aa3b, v17
	v_exp_f32_e32 v19, v19
	s_nop 0
	v_add_f32_e32 v19, 1.0, v19
	v_rcp_f32_e32 v19, v19
	s_nop 0
	v_mul_f32_e32 v17, v17, v19
	v_mul_f32_e32 v16, v16, v17
	v_mov_b32_dpp v24, v93 row_ror:2 row_mask:0xf bank_mask:0xf
	v_mov_b32_dpp v34, v92 row_ror:2 row_mask:0xf bank_mask:0xf
	v_mov_b32_dpp v19, v93 row_ror:1 row_mask:0xf bank_mask:0xf
	v_mov_b32_dpp v33, v92 row_ror:1 row_mask:0xf bank_mask:0xf
	v_cndmask_b32_e64 v23, v27, v24, s[40:41]
	v_cndmask_b32_e64 v22, v32, v34, s[40:41]
	v_cndmask_b32_e64 v21, v19, v25, s[38:39]
	v_cndmask_b32_e64 v20, v33, v31, s[38:39]
	v_pk_fma_f32 v[22:23], v[14:15], v[22:23], v[8:9]
	v_pk_fma_f32 v[20:21], v[6:7], v[20:21], v[22:23]
	v_pk_fma_f32 v[20:21], v[10:11], v[92:93], v[20:21]
	v_mul_f32_e32 v17, 0xbfb8aa3b, v21
	v_exp_f32_e32 v17, v17
	s_nop 0
	v_add_f32_e32 v17, 1.0, v17
	v_rcp_f32_e32 v17, v17
	s_nop 0
	v_mul_f32_e32 v17, v21, v17
	v_mul_f32_e32 v17, v20, v17
	v_mov_b32_dpp v27, v77 row_ror:2 row_mask:0xf bank_mask:0xf
	v_mov_b32_dpp v32, v76 row_ror:2 row_mask:0xf bank_mask:0xf
	v_mov_b32_dpp v25, v77 row_ror:1 row_mask:0xf bank_mask:0xf
	v_mov_b32_dpp v31, v76 row_ror:1 row_mask:0xf bank_mask:0xf
	v_cndmask_b32_e64 v23, v24, v27, s[40:41]
	v_cndmask_b32_e64 v22, v34, v32, s[40:41]
	v_cndmask_b32_e64 v21, v25, v19, s[38:39]
	v_cndmask_b32_e64 v20, v31, v33, s[38:39]
	v_pk_fma_f32 v[22:23], v[14:15], v[22:23], v[8:9]
	v_pk_fma_f32 v[20:21], v[6:7], v[20:21], v[22:23]
	v_pk_fma_f32 v[20:21], v[10:11], v[76:77], v[20:21]
	v_mul_f32_e32 v19, 0xbfb8aa3b, v21
	v_exp_f32_e32 v19, v19
	s_nop 0
	v_add_f32_e32 v19, 1.0, v19
	v_rcp_f32_e32 v19, v19
	s_nop 0
	v_mul_f32_e32 v19, v21, v19
	v_mul_f32_e32 v19, v20, v19
	v_mov_b32_dpp v33, v61 row_ror:2 row_mask:0xf bank_mask:0xf
	v_mov_b32_dpp v35, v60 row_ror:2 row_mask:0xf bank_mask:0xf
	v_mov_b32_dpp v24, v61 row_ror:1 row_mask:0xf bank_mask:0xf
	v_mov_b32_dpp v34, v60 row_ror:1 row_mask:0xf bank_mask:0xf
	v_cndmask_b32_e64 v23, v27, v33, s[40:41]
	v_cndmask_b32_e64 v22, v32, v35, s[40:41]
	v_cndmask_b32_e64 v21, v24, v25, s[38:39]
	v_cndmask_b32_e64 v20, v34, v31, s[38:39]
	v_pk_fma_f32 v[22:23], v[14:15], v[22:23], v[8:9]
	v_pk_fma_f32 v[20:21], v[6:7], v[20:21], v[22:23]
	v_pk_fma_f32 v[20:21], v[10:11], v[60:61], v[20:21]
	v_mul_f32_e32 v22, 0xbfb8aa3b, v21
	v_exp_f32_e32 v22, v22
	s_nop 0
	v_add_f32_e32 v22, 1.0, v22
	v_rcp_f32_e32 v22, v22
	s_nop 0
	v_mul_f32_e32 v21, v21, v22
	v_mul_f32_e32 v20, v20, v21
	v_mov_b32_dpp v27, v45 row_ror:1 row_mask:0xf bank_mask:0xf
	v_mov_b32_dpp v31, v45 row_ror:2 row_mask:0xf bank_mask:0xf
	v_mov_b32_dpp v36, v44 row_ror:2 row_mask:0xf bank_mask:0xf
	v_mov_b32_dpp v32, v44 row_ror:1 row_mask:0xf bank_mask:0xf
	v_cndmask_b32_e64 v23, v27, v24, s[38:39]
	v_cndmask_b32_e64 v25, v33, v31, s[40:41]
	v_cndmask_b32_e64 v24, v35, v36, s[40:41]
	v_cndmask_b32_e64 v22, v32, v34, s[38:39]
	v_pk_fma_f32 v[24:25], v[14:15], v[24:25], v[8:9]
	s_nop 0
	v_pk_fma_f32 v[22:23], v[6:7], v[22:23], v[24:25]
	v_pk_fma_f32 v[22:23], v[10:11], v[44:45], v[22:23]
	s_nop 0
	v_mul_f32_e32 v21, 0xbfb8aa3b, v23
	v_exp_f32_e32 v21, v21
	s_nop 0
	v_add_f32_e32 v21, 1.0, v21
	v_rcp_f32_e32 v21, v21
	s_nop 0
	v_mul_f32_e32 v21, v23, v21
	v_mul_f32_e32 v24, v22, v21
	v_mov_b32_dpp v22, v29 row_ror:2 row_mask:0xf bank_mask:0xf
	v_mov_b32_dpp v25, v28 row_ror:2 row_mask:0xf bank_mask:0xf
	v_mov_b32_dpp v21, v29 row_ror:1 row_mask:0xf bank_mask:0xf
	v_mov_b32_dpp v23, v28 row_ror:1 row_mask:0xf bank_mask:0xf
	v_cndmask_b32_e64 v35, v31, v22, s[40:41]
	v_cndmask_b32_e64 v34, v36, v25, s[40:41]
	v_cndmask_b32_e64 v33, v21, v27, s[38:39]
	v_cndmask_b32_e64 v32, v23, v32, s[38:39]
	v_pk_fma_f32 v[34:35], v[14:15], v[34:35], v[8:9]
	v_pk_fma_f32 v[32:33], v[6:7], v[32:33], v[34:35]
	s_nop 0
	v_pk_fma_f32 v[28:29], v[10:11], v[28:29], v[32:33]
	v_mul_f32_e32 v27, 0xbfb8aa3b, v29
	v_exp_f32_e32 v27, v27
	s_nop 0
	v_add_f32_e32 v27, 1.0, v27
	v_rcp_f32_e32 v27, v27
	s_nop 0
	v_mul_f32_e32 v27, v29, v27
	v_mul_f32_e32 v27, v28, v27
	s_nop 0
	v_mov_b32_dpp v28, v13 row_ror:1 row_mask:0xf bank_mask:0xf
	v_mov_b32_dpp v29, v13 row_ror:2 row_mask:0xf bank_mask:0xf
	v_mov_b32_dpp v31, v12 row_ror:1 row_mask:0xf bank_mask:0xf
	v_mov_b32_dpp v32, v12 row_ror:2 row_mask:0xf bank_mask:0xf
	v_cmp_gt_i32_e32 vcc, s97, v198
	s_and_b64 s[44:45], s[40:41], vcc
	s_and_saveexec_b64 s[34:35], s[44:45]
	s_cbranch_execz .LBB0_45
	v_cvt_pk_bf16_f32 v37, v39, v18
	v_add_u32_e32 v18, s20, v198
	v_mov_b64_e32 v[44:45], s[8:9]
	s_movk_i32 s21, 0x1600
	v_mad_i64_i32 v[44:45], s[44:45], v18, s21, v[44:45]
	v_cvt_pk_bf16_f32 v34, v184, v137
	v_cvt_pk_bf16_f32 v35, v99, v63
	v_cvt_pk_bf16_f32 v36, v56, v43
	v_lshl_add_u64 v[44:45], v[4:5], 1, v[44:45]
	flat_store_dwordx4 v[44:45], v[34:37]
